# stick-breaking unit: hand-written tile math with wide independent batches, K/V of these layers in a tile-contiguous image, gate chunks requested in the unit header, 16-byte epilogue stores via permlan
# speedup vs baseline: 1.0269x; 1.0150x over previous
; __device__ __forceinline__ unsigned cvt_pk_bf16(float lo, float hi) { f32x2_t v = {lo, hi}; bf16x2_t b = __builtin_convertvector(v, bf16x2_t); return __builtin_bit_cast(unsigned, b); }
;     __device__ __forceinline__ void operator()(const f32x4 (&acc)[2][2][4][2], const Unit& u, int wr, int wc, int fr, int fq) const {
;     ...
;         } else {
; #pragma unroll
;         for (int ai = 0; ai < 2; ++ai)
; #pragma unroll
;             for (int m = 0; m < 4; ++m) { bf16_t* rowp = O + (size_t)(row0 + ai * HALF + m * 16) * ldc + col0;
; #pragma unroll
;                 for (int bj = 0; bj < 2; ++bj) { const f32x4 v0 = acc[ai][bj][m][0], v1 = acc[ai][bj][m][1];
;                     u32x4 w; w.x = cvt_pk_bf16(v0[0], v0[1]); w.y = cvt_pk_bf16(v0[2], v0[3]); w.z = cvt_pk_bf16(v1[0], v1[1]); w.w = cvt_pk_bf16(v1[2], v1[3]);
;                     *(u32x4*)(rowp + bj * HALF) = w; } }
.LBB0_131:
	v_writelane_b32 v232, 0, 62
	s_cmp_lt_i32 s94, 4
	v_lshl_add_u32 v136, s20, 8, v151
	s_waitcnt lgkmcnt(0)
	v_lshl_or_b32 v132, s94, 8, v152
	s_cselect_b64 s[10:11], -1, 0
	s_and_b64 s[22:23], s[16:17], s[10:11]
	v_ashrrev_i32_e32 v133, 31, v132
	v_or_b32_e32 v144, 16, v136
	v_or_b32_e32 v142, 32, v136
	v_or_b32_e32 v138, 48, v136
	v_ashrrev_i32_e32 v137, 31, v136
	s_mov_b64 s[10:11], -1
	s_and_b64 vcc, exec, s[22:23]
	v_lshlrev_b64 v[134:135], 1, v[132:133]
	v_ashrrev_i32_e32 v145, 31, v144
	v_ashrrev_i32_e32 v143, 31, v142
	v_ashrrev_i32_e32 v139, 31, v138
	s_cbranch_vccnz .LBB0_133
	v_readlane_b32 s10, v232, 48
	s_nop 3
	s_and_b32 s10, s10, 3
	s_cmp_lg_u32 s10, 0
	s_cbranch_scc1 .Lkv_no
	s_sub_i32 s10, s94, 4
	s_cmp_lt_u32 s10, 8
	s_cbranch_scc0 .Lkv_no
	s_mov_b32 s10, 1
	v_writelane_b32 v232, s10, 62
	s_branch .Lkv_epi
.Lkv_no:
	v_lshlrev_b64 v[146:147], s63, v[136:137]
	v_lshl_add_u64 v[146:147], v[146:147], 1, s[24:25]
	v_lshl_add_u64 v[146:147], v[146:147], 0, v[134:135]
	v_cvt_pk_bf16_f32 v168, v126, v127
	v_cvt_pk_bf16_f32 v169, v128, v129
	v_cvt_pk_bf16_f32 v170, v122, v123
	v_cvt_pk_bf16_f32 v171, v124, v125
	global_store_dwordx4 v[146:147], v[168:171], off
	s_mov_b64 s[10:11], 0
	s_nop 0
	v_cvt_pk_bf16_f32 v168, v114, v115
	v_cvt_pk_bf16_f32 v169, v116, v117
	v_cvt_pk_bf16_f32 v170, v106, v107
	v_cvt_pk_bf16_f32 v171, v108, v109
	global_store_dwordx4 v[146:147], v[168:171], off offset:256
	v_lshlrev_b64 v[146:147], s63, v[144:145]
	v_lshl_add_u64 v[146:147], v[146:147], 1, s[24:25]
	v_lshl_add_u64 v[146:147], v[146:147], 0, v[134:135]
	v_cvt_pk_bf16_f32 v168, v118, v119
	v_cvt_pk_bf16_f32 v169, v120, v121
	v_cvt_pk_bf16_f32 v170, v110, v111
	v_cvt_pk_bf16_f32 v171, v112, v113
	global_store_dwordx4 v[146:147], v[168:171], off
	s_nop 1
	v_cvt_pk_bf16_f32 v168, v98, v99
	v_cvt_pk_bf16_f32 v169, v100, v101
	v_cvt_pk_bf16_f32 v170, v90, v91
	v_cvt_pk_bf16_f32 v171, v92, v93
	global_store_dwordx4 v[146:147], v[168:171], off offset:256
	v_lshlrev_b64 v[146:147], s63, v[142:143]
	v_lshl_add_u64 v[146:147], v[146:147], 1, s[24:25]
	v_lshl_add_u64 v[146:147], v[146:147], 0, v[134:135]
	v_cvt_pk_bf16_f32 v168, v102, v103
	v_cvt_pk_bf16_f32 v169, v104, v105
	v_cvt_pk_bf16_f32 v170, v94, v95
	v_cvt_pk_bf16_f32 v171, v96, v97
	global_store_dwordx4 v[146:147], v[168:171], off
	s_nop 1
	v_cvt_pk_bf16_f32 v168, v82, v83
	v_cvt_pk_bf16_f32 v169, v84, v85
	v_cvt_pk_bf16_f32 v170, v74, v75
	v_cvt_pk_bf16_f32 v171, v76, v77
	global_store_dwordx4 v[146:147], v[168:171], off offset:256
	v_lshlrev_b64 v[146:147], s63, v[138:139]
	v_lshl_add_u64 v[146:147], v[146:147], 1, s[24:25]
	v_lshl_add_u64 v[146:147], v[146:147], 0, v[134:135]
	v_cvt_pk_bf16_f32 v168, v86, v87
	v_cvt_pk_bf16_f32 v169, v88, v89
	v_cvt_pk_bf16_f32 v170, v78, v79
	v_cvt_pk_bf16_f32 v171, v80, v81
	global_store_dwordx4 v[146:147], v[168:171], off
	s_nop 1
	v_cvt_pk_bf16_f32 v168, v70, v71
	v_cvt_pk_bf16_f32 v169, v72, v73
	v_cvt_pk_bf16_f32 v170, v66, v67
	v_cvt_pk_bf16_f32 v171, v68, v69
	global_store_dwordx4 v[146:147], v[168:171], off offset:256
	v_add_u32_e32 v146, 0x80, v136
	v_ashrrev_i32_e32 v147, 31, v146
	v_lshlrev_b64 v[146:147], s63, v[146:147]
	v_lshl_add_u64 v[146:147], v[146:147], 1, s[24:25]
	v_lshl_add_u64 v[146:147], v[146:147], 0, v[134:135]
	v_cvt_pk_bf16_f32 v168, v62, v63
	v_cvt_pk_bf16_f32 v169, v64, v65
	v_cvt_pk_bf16_f32 v170, v58, v59
	v_cvt_pk_bf16_f32 v171, v60, v61
	global_store_dwordx4 v[146:147], v[168:171], off
	s_nop 1
	v_cvt_pk_bf16_f32 v168, v50, v51
	v_cvt_pk_bf16_f32 v169, v52, v53
	v_cvt_pk_bf16_f32 v170, v42, v43
	v_cvt_pk_bf16_f32 v171, v44, v45
	global_store_dwordx4 v[146:147], v[168:171], off offset:256
	v_add_u32_e32 v146, 0x90, v136
	v_ashrrev_i32_e32 v147, 31, v146
	v_lshlrev_b64 v[146:147], s63, v[146:147]
	v_lshl_add_u64 v[146:147], v[146:147], 1, s[24:25]
	v_lshl_add_u64 v[146:147], v[146:147], 0, v[134:135]
	v_cvt_pk_bf16_f32 v168, v54, v55
	v_cvt_pk_bf16_f32 v169, v56, v57
	v_cvt_pk_bf16_f32 v170, v46, v47
	v_cvt_pk_bf16_f32 v171, v48, v49
	global_store_dwordx4 v[146:147], v[168:171], off
	s_nop 1
	v_cvt_pk_bf16_f32 v168, v34, v35
	v_cvt_pk_bf16_f32 v169, v36, v37
	v_cvt_pk_bf16_f32 v170, v26, v27
	v_cvt_pk_bf16_f32 v171, v28, v29
	global_store_dwordx4 v[146:147], v[168:171], off offset:256
	v_add_u32_e32 v146, 0xa0, v136
	v_ashrrev_i32_e32 v147, 31, v146
	v_lshlrev_b64 v[146:147], s63, v[146:147]
	v_lshl_add_u64 v[146:147], v[146:147], 1, s[24:25]
	v_lshl_add_u64 v[146:147], v[146:147], 0, v[134:135]
	v_cvt_pk_bf16_f32 v168, v38, v39
	v_cvt_pk_bf16_f32 v169, v40, v41
	v_cvt_pk_bf16_f32 v170, v30, v31
	v_cvt_pk_bf16_f32 v171, v32, v33
	global_store_dwordx4 v[146:147], v[168:171], off
	s_nop 1
	v_cvt_pk_bf16_f32 v168, v18, v19
	v_cvt_pk_bf16_f32 v169, v20, v21
	v_cvt_pk_bf16_f32 v170, v10, v11
	v_cvt_pk_bf16_f32 v171, v12, v13
	global_store_dwordx4 v[146:147], v[168:171], off offset:256
	v_add_u32_e32 v146, 0xb0, v136
	v_ashrrev_i32_e32 v147, 31, v146
	v_lshlrev_b64 v[146:147], s63, v[146:147]
	v_lshl_add_u64 v[146:147], v[146:147], 1, s[24:25]
	v_lshl_add_u64 v[158:159], v[146:147], 0, v[134:135]
	v_cvt_pk_bf16_f32 v168, v22, v23
	v_cvt_pk_bf16_f32 v169, v24, v25
	v_cvt_pk_bf16_f32 v170, v14, v15
	v_cvt_pk_bf16_f32 v171, v16, v17
	global_store_dwordx4 v[158:159], v[168:171], off

; __device__ __forceinline__ unsigned cvt_pk_bf16(float lo, float hi) { f32x2_t v = {lo, hi}; bf16x2_t b = __builtin_convertvector(v, bf16x2_t); return __builtin_bit_cast(unsigned, b); }
;     __device__ __forceinline__ void operator()(const f32x4 (&acc)[2][2][4][2], const Unit& u, int wr, int wc, int fr, int fq) const {
;     ...
;             for (int m = 0; m < 4; ++m) { bf16_t* rowp = O + (size_t)(row0 + ai * HALF + m * 16) * ldc + col0;
; #pragma unroll
;                 for (int bj = 0; bj < 2; ++bj) { const f32x4 v0 = acc[ai][bj][m][0], v1 = acc[ai][bj][m][1];
;                     u32x4 w; w.x = cvt_pk_bf16(v0[0], v0[1]); w.y = cvt_pk_bf16(v0[2], v0[3]); w.z = cvt_pk_bf16(v1[0], v1[1]); w.w = cvt_pk_bf16(v1[2], v1[3]);
;                     *(u32x4*)(rowp + bj * HALF) = w; } }
.LBB0_135:
	s_nop 1
	v_lshl_add_u64 v[10:11], v[132:133], 1, v[146:147]
	v_cvt_pk_bf16_f32 v6, v6, v7
	v_cvt_pk_bf16_f32 v7, v8, v9
	v_cvt_pk_bf16_f32 v8, v2, v3
	v_cvt_pk_bf16_f32 v9, v4, v5
	v_readlane_b32 s10, v232, 62
	s_nop 3
	s_cmp_eq_u32 s10, 0
	s_cbranch_scc1 .Lkv_tail_plain
	s_andn2_b64 vcc, exec, s[6:7]
	s_mov_b64 s[6:7], -1
	v_subrev_u32_e32 v234, s24, v10
	v_add_u32_e32 v234, 0x100, v234
	v_lshrrev_b32_e32 v235, 13, v234
	v_and_b32_e32 v236, 0x7f, v234
	v_bfe_u32 v237, v234, 7, 4
	v_bfe_u32 v238, v234, 12, 1
	v_lshrrev_b32_e32 v239, 13, v235
	v_lshl_add_u32 v239, v239, 4, v237
	v_bfe_u32 v237, v235, 6, 7
	v_lshl_add_u32 v239, v239, 7, v237
	v_lshl_add_u32 v239, v238, 13, v239
	v_bfe_u32 v237, v235, 5, 1
	v_lshl_add_u32 v239, v239, 1, v237
	v_and_b32_e32 v237, 31, v235
	v_lshl_add_u32 v236, v237, 7, v236
	v_lshl_add_u32 v236, v239, 13, v236
	v_add_u32_e32 v236, 0x800, v236
	v_mov_b32_e32 v237, 0
	v_lshl_add_u64 v[236:237], s[24:25], 0, v[236:237]
	global_store_dwordx4 v[236:237], v[6:9], off
	s_cbranch_vccnz .LBB0_109
	s_branch .Lkv_after
.Lkv_tail_plain:
	s_andn2_b64 vcc, exec, s[6:7]
	s_mov_b64 s[6:7], -1
	global_store_dwordx4 v[10:11], v[6:9], off offset:256
	s_cbranch_vccnz .LBB0_109
.Lkv_after:
	s_andn2_b64 vcc, exec, s[18:19]
	s_cbranch_vccnz .LBB0_108
	s_barrier
	s_branch .LBB0_108
.Lkv_epi:
	v_lshlrev_b64 v[146:147], s63, v[136:137]
	v_lshl_add_u64 v[146:147], v[146:147], 1, s[24:25]
	v_lshl_add_u64 v[146:147], v[146:147], 0, v[134:135]
	v_cvt_pk_bf16_f32 v168, v126, v127
	v_cvt_pk_bf16_f32 v169, v128, v129
	v_cvt_pk_bf16_f32 v170, v122, v123
	v_cvt_pk_bf16_f32 v171, v124, v125
	v_subrev_u32_e32 v234, s24, v146
	v_lshrrev_b32_e32 v235, 13, v234
	v_and_b32_e32 v236, 0x7f, v234
	v_bfe_u32 v237, v234, 7, 4
	v_bfe_u32 v238, v234, 12, 1
	v_lshrrev_b32_e32 v239, 13, v235
	v_lshl_add_u32 v239, v239, 4, v237
	v_bfe_u32 v237, v235, 6, 7
	v_lshl_add_u32 v239, v239, 7, v237
	v_lshl_add_u32 v239, v238, 13, v239
	v_bfe_u32 v237, v235, 5, 1
	v_lshl_add_u32 v239, v239, 1, v237
	v_and_b32_e32 v237, 31, v235
	v_lshl_add_u32 v236, v237, 7, v236
	v_lshl_add_u32 v236, v239, 13, v236
	v_add_u32_e32 v236, 0x800, v236
	v_mov_b32_e32 v237, 0
	v_lshl_add_u64 v[236:237], s[24:25], 0, v[236:237]
	global_store_dwordx4 v[236:237], v[168:171], off
	s_mov_b64 s[10:11], 0
	s_nop 0
	v_cvt_pk_bf16_f32 v168, v114, v115
	v_cvt_pk_bf16_f32 v169, v116, v117
	v_cvt_pk_bf16_f32 v170, v106, v107
	v_cvt_pk_bf16_f32 v171, v108, v109
	v_subrev_u32_e32 v234, s24, v146
	v_add_u32_e32 v234, 0x100, v234
	v_lshrrev_b32_e32 v235, 13, v234
	v_and_b32_e32 v236, 0x7f, v234
	v_bfe_u32 v237, v234, 7, 4
	v_bfe_u32 v238, v234, 12, 1
	v_lshrrev_b32_e32 v239, 13, v235
	v_lshl_add_u32 v239, v239, 4, v237
	v_bfe_u32 v237, v235, 6, 7
	v_lshl_add_u32 v239, v239, 7, v237
	v_lshl_add_u32 v239, v238, 13, v239
	v_bfe_u32 v237, v235, 5, 1
	v_lshl_add_u32 v239, v239, 1, v237
	v_and_b32_e32 v237, 31, v235
	v_lshl_add_u32 v236, v237, 7, v236
	v_lshl_add_u32 v236, v239, 13, v236
	v_add_u32_e32 v236, 0x800, v236
	v_mov_b32_e32 v237, 0
	v_lshl_add_u64 v[236:237], s[24:25], 0, v[236:237]
	global_store_dwordx4 v[236:237], v[168:171], off
	v_lshlrev_b64 v[146:147], s63, v[144:145]
	v_lshl_add_u64 v[146:147], v[146:147], 1, s[24:25]
	v_lshl_add_u64 v[146:147], v[146:147], 0, v[134:135]
	v_cvt_pk_bf16_f32 v168, v118, v119
	v_cvt_pk_bf16_f32 v169, v120, v121
	v_cvt_pk_bf16_f32 v170, v110, v111
	v_cvt_pk_bf16_f32 v171, v112, v113
	v_subrev_u32_e32 v234, s24, v146
	v_lshrrev_b32_e32 v235, 13, v234
	v_and_b32_e32 v236, 0x7f, v234
	v_bfe_u32 v237, v234, 7, 4
	v_bfe_u32 v238, v234, 12, 1
	v_lshrrev_b32_e32 v239, 13, v235
	v_lshl_add_u32 v239, v239, 4, v237
	v_bfe_u32 v237, v235, 6, 7
	v_lshl_add_u32 v239, v239, 7, v237
	v_lshl_add_u32 v239, v238, 13, v239
	v_bfe_u32 v237, v235, 5, 1
	v_lshl_add_u32 v239, v239, 1, v237
	v_and_b32_e32 v237, 31, v235
	v_lshl_add_u32 v236, v237, 7, v236
	v_lshl_add_u32 v236, v239, 13, v236
	v_add_u32_e32 v236, 0x800, v236
	v_mov_b32_e32 v237, 0
	v_lshl_add_u64 v[236:237], s[24:25], 0, v[236:237]
	global_store_dwordx4 v[236:237], v[168:171], off
	s_nop 1
	v_cvt_pk_bf16_f32 v168, v98, v99
	v_cvt_pk_bf16_f32 v169, v100, v101
	v_cvt_pk_bf16_f32 v170, v90, v91
	v_cvt_pk_bf16_f32 v171, v92, v93
	v_subrev_u32_e32 v234, s24, v146
	v_add_u32_e32 v234, 0x100, v234
	v_lshrrev_b32_e32 v235, 13, v234
	v_and_b32_e32 v236, 0x7f, v234
	v_bfe_u32 v237, v234, 7, 4
	v_bfe_u32 v238, v234, 12, 1
	v_lshrrev_b32_e32 v239, 13, v235
	v_lshl_add_u32 v239, v239, 4, v237
	v_bfe_u32 v237, v235, 6, 7
	v_lshl_add_u32 v239, v239, 7, v237
	v_lshl_add_u32 v239, v238, 13, v239
	v_bfe_u32 v237, v235, 5, 1
	v_lshl_add_u32 v239, v239, 1, v237
	v_and_b32_e32 v237, 31, v235
	v_lshl_add_u32 v236, v237, 7, v236
	v_lshl_add_u32 v236, v239, 13, v236
	v_add_u32_e32 v236, 0x800, v236
	v_mov_b32_e32 v237, 0
	v_lshl_add_u64 v[236:237], s[24:25], 0, v[236:237]
	global_store_dwordx4 v[236:237], v[168:171], off
	v_lshlrev_b64 v[146:147], s63, v[142:143]
	v_lshl_add_u64 v[146:147], v[146:147], 1, s[24:25]
	v_lshl_add_u64 v[146:147], v[146:147], 0, v[134:135]
	v_cvt_pk_bf16_f32 v168, v102, v103
	v_cvt_pk_bf16_f32 v169, v104, v105
	v_cvt_pk_bf16_f32 v170, v94, v95
	v_cvt_pk_bf16_f32 v171, v96, v97
	v_subrev_u32_e32 v234, s24, v146
	v_lshrrev_b32_e32 v235, 13, v234
	v_and_b32_e32 v236, 0x7f, v234
	v_bfe_u32 v237, v234, 7, 4
	v_bfe_u32 v238, v234, 12, 1
	v_lshrrev_b32_e32 v239, 13, v235
	v_lshl_add_u32 v239, v239, 4, v237
	v_bfe_u32 v237, v235, 6, 7
	v_lshl_add_u32 v239, v239, 7, v237
	v_lshl_add_u32 v239, v238, 13, v239
	v_bfe_u32 v237, v235, 5, 1
	v_lshl_add_u32 v239, v239, 1, v237
	v_and_b32_e32 v237, 31, v235
; __device__ __forceinline__ unsigned cvt_pk_bf16(float lo, float hi) { f32x2_t v = {lo, hi}; bf16x2_t b = __builtin_convertvector(v, bf16x2_t); return __builtin_bit_cast(unsigned, b); }
;     __device__ __forceinline__ void operator()(const f32x4 (&acc)[2][2][4][2], const Unit& u, int wr, int wc, int fr, int fq) const {
;     ...
;             for (int m = 0; m < 4; ++m) { bf16_t* rowp = O + (size_t)(row0 + ai * HALF + m * 16) * ldc + col0;
; #pragma unroll
;                 for (int bj = 0; bj < 2; ++bj) { const f32x4 v0 = acc[ai][bj][m][0], v1 = acc[ai][bj][m][1];
;                     u32x4 w; w.x = cvt_pk_bf16(v0[0], v0[1]); w.y = cvt_pk_bf16(v0[2], v0[3]); w.z = cvt_pk_bf16(v1[0], v1[1]); w.w = cvt_pk_bf16(v1[2], v1[3]);
;                     *(u32x4*)(rowp + bj * HALF) = w; } }
	v_lshl_add_u32 v236, v237, 7, v236
	v_lshl_add_u32 v236, v239, 13, v236
	v_add_u32_e32 v236, 0x800, v236
	v_mov_b32_e32 v237, 0
	v_lshl_add_u64 v[236:237], s[24:25], 0, v[236:237]
	global_store_dwordx4 v[236:237], v[168:171], off
	s_nop 1
	v_cvt_pk_bf16_f32 v168, v82, v83
	v_cvt_pk_bf16_f32 v169, v84, v85
	v_cvt_pk_bf16_f32 v170, v74, v75
	v_cvt_pk_bf16_f32 v171, v76, v77
	v_subrev_u32_e32 v234, s24, v146
	v_add_u32_e32 v234, 0x100, v234
	v_lshrrev_b32_e32 v235, 13, v234
	v_and_b32_e32 v236, 0x7f, v234
	v_bfe_u32 v237, v234, 7, 4
	v_bfe_u32 v238, v234, 12, 1
	v_lshrrev_b32_e32 v239, 13, v235
	v_lshl_add_u32 v239, v239, 4, v237
	v_bfe_u32 v237, v235, 6, 7
	v_lshl_add_u32 v239, v239, 7, v237
	v_lshl_add_u32 v239, v238, 13, v239
	v_bfe_u32 v237, v235, 5, 1
	v_lshl_add_u32 v239, v239, 1, v237
	v_and_b32_e32 v237, 31, v235
	v_lshl_add_u32 v236, v237, 7, v236
	v_lshl_add_u32 v236, v239, 13, v236
	v_add_u32_e32 v236, 0x800, v236
	v_mov_b32_e32 v237, 0
	v_lshl_add_u64 v[236:237], s[24:25], 0, v[236:237]
	global_store_dwordx4 v[236:237], v[168:171], off
	v_lshlrev_b64 v[146:147], s63, v[138:139]
	v_lshl_add_u64 v[146:147], v[146:147], 1, s[24:25]
	v_lshl_add_u64 v[146:147], v[146:147], 0, v[134:135]
	v_cvt_pk_bf16_f32 v168, v86, v87
	v_cvt_pk_bf16_f32 v169, v88, v89
	v_cvt_pk_bf16_f32 v170, v78, v79
	v_cvt_pk_bf16_f32 v171, v80, v81
	v_subrev_u32_e32 v234, s24, v146
	v_lshrrev_b32_e32 v235, 13, v234
	v_and_b32_e32 v236, 0x7f, v234
	v_bfe_u32 v237, v234, 7, 4
	v_bfe_u32 v238, v234, 12, 1
	v_lshrrev_b32_e32 v239, 13, v235
	v_lshl_add_u32 v239, v239, 4, v237
	v_bfe_u32 v237, v235, 6, 7
	v_lshl_add_u32 v239, v239, 7, v237
	v_lshl_add_u32 v239, v238, 13, v239
	v_bfe_u32 v237, v235, 5, 1
	v_lshl_add_u32 v239, v239, 1, v237
	v_and_b32_e32 v237, 31, v235
	v_lshl_add_u32 v236, v237, 7, v236
	v_lshl_add_u32 v236, v239, 13, v236
	v_add_u32_e32 v236, 0x800, v236
	v_mov_b32_e32 v237, 0
	v_lshl_add_u64 v[236:237], s[24:25], 0, v[236:237]
	global_store_dwordx4 v[236:237], v[168:171], off
	s_nop 1
	v_cvt_pk_bf16_f32 v168, v70, v71
	v_cvt_pk_bf16_f32 v169, v72, v73
	v_cvt_pk_bf16_f32 v170, v66, v67
	v_cvt_pk_bf16_f32 v171, v68, v69
	v_subrev_u32_e32 v234, s24, v146
	v_add_u32_e32 v234, 0x100, v234
	v_lshrrev_b32_e32 v235, 13, v234
	v_and_b32_e32 v236, 0x7f, v234
	v_bfe_u32 v237, v234, 7, 4
	v_bfe_u32 v238, v234, 12, 1
	v_lshrrev_b32_e32 v239, 13, v235
	v_lshl_add_u32 v239, v239, 4, v237
	v_bfe_u32 v237, v235, 6, 7
	v_lshl_add_u32 v239, v239, 7, v237
	v_lshl_add_u32 v239, v238, 13, v239
	v_bfe_u32 v237, v235, 5, 1
	v_lshl_add_u32 v239, v239, 1, v237
	v_and_b32_e32 v237, 31, v235
	v_lshl_add_u32 v236, v237, 7, v236
	v_lshl_add_u32 v236, v239, 13, v236
	v_add_u32_e32 v236, 0x800, v236
	v_mov_b32_e32 v237, 0
	v_lshl_add_u64 v[236:237], s[24:25], 0, v[236:237]
	global_store_dwordx4 v[236:237], v[168:171], off
	v_add_u32_e32 v146, 0x80, v136
	v_ashrrev_i32_e32 v147, 31, v146
	v_lshlrev_b64 v[146:147], s63, v[146:147]
	v_lshl_add_u64 v[146:147], v[146:147], 1, s[24:25]
	v_lshl_add_u64 v[146:147], v[146:147], 0, v[134:135]
	v_cvt_pk_bf16_f32 v168, v62, v63
	v_cvt_pk_bf16_f32 v169, v64, v65
	v_cvt_pk_bf16_f32 v170, v58, v59
	v_cvt_pk_bf16_f32 v171, v60, v61
	v_subrev_u32_e32 v234, s24, v146
	v_lshrrev_b32_e32 v235, 13, v234
	v_and_b32_e32 v236, 0x7f, v234
	v_bfe_u32 v237, v234, 7, 4
	v_bfe_u32 v238, v234, 12, 1
	v_lshrrev_b32_e32 v239, 13, v235
	v_lshl_add_u32 v239, v239, 4, v237
	v_bfe_u32 v237, v235, 6, 7
	v_lshl_add_u32 v239, v239, 7, v237
	v_lshl_add_u32 v239, v238, 13, v239
	v_bfe_u32 v237, v235, 5, 1
	v_lshl_add_u32 v239, v239, 1, v237
	v_and_b32_e32 v237, 31, v235
	v_lshl_add_u32 v236, v237, 7, v236
	v_lshl_add_u32 v236, v239, 13, v236
	v_add_u32_e32 v236, 0x800, v236
	v_mov_b32_e32 v237, 0
	v_lshl_add_u64 v[236:237], s[24:25], 0, v[236:237]
	global_store_dwordx4 v[236:237], v[168:171], off
	s_nop 1
	v_cvt_pk_bf16_f32 v168, v50, v51
	v_cvt_pk_bf16_f32 v169, v52, v53
	v_cvt_pk_bf16_f32 v170, v42, v43
	v_cvt_pk_bf16_f32 v171, v44, v45
	v_subrev_u32_e32 v234, s24, v146
	v_add_u32_e32 v234, 0x100, v234
	v_lshrrev_b32_e32 v235, 13, v234
	v_and_b32_e32 v236, 0x7f, v234
	v_bfe_u32 v237, v234, 7, 4
	v_bfe_u32 v238, v234, 12, 1
	v_lshrrev_b32_e32 v239, 13, v235
	v_lshl_add_u32 v239, v239, 4, v237
	v_bfe_u32 v237, v235, 6, 7
	v_lshl_add_u32 v239, v239, 7, v237
	v_lshl_add_u32 v239, v238, 13, v239
	v_bfe_u32 v237, v235, 5, 1
	v_lshl_add_u32 v239, v239, 1, v237
	v_and_b32_e32 v237, 31, v235
	v_lshl_add_u32 v236, v237, 7, v236
	v_lshl_add_u32 v236, v239, 13, v236
	v_add_u32_e32 v236, 0x800, v236
	v_mov_b32_e32 v237, 0
	v_lshl_add_u64 v[236:237], s[24:25], 0, v[236:237]
	global_store_dwordx4 v[236:237], v[168:171], off
; __device__ __forceinline__ unsigned cvt_pk_bf16(float lo, float hi) { f32x2_t v = {lo, hi}; bf16x2_t b = __builtin_convertvector(v, bf16x2_t); return __builtin_bit_cast(unsigned, b); }
;     __device__ __forceinline__ void operator()(const f32x4 (&acc)[2][2][4][2], const Unit& u, int wr, int wc, int fr, int fq) const {
;     ...
; #pragma unroll
;         for (int ai = 0; ai < 2; ++ai)
; #pragma unroll
;             for (int m = 0; m < 4; ++m) { bf16_t* rowp = O + (size_t)(row0 + ai * HALF + m * 16) * ldc + col0;
; #pragma unroll
;                 for (int bj = 0; bj < 2; ++bj) { const f32x4 v0 = acc[ai][bj][m][0], v1 = acc[ai][bj][m][1];
;                     u32x4 w; w.x = cvt_pk_bf16(v0[0], v0[1]); w.y = cvt_pk_bf16(v0[2], v0[3]); w.z = cvt_pk_bf16(v1[0], v1[1]); w.w = cvt_pk_bf16(v1[2], v1[3]);
;                     *(u32x4*)(rowp + bj * HALF) = w; } }
	v_add_u32_e32 v146, 0x90, v136
	v_ashrrev_i32_e32 v147, 31, v146
	v_lshlrev_b64 v[146:147], s63, v[146:147]
	v_lshl_add_u64 v[146:147], v[146:147], 1, s[24:25]
	v_lshl_add_u64 v[146:147], v[146:147], 0, v[134:135]
	v_cvt_pk_bf16_f32 v168, v54, v55
	v_cvt_pk_bf16_f32 v169, v56, v57
	v_cvt_pk_bf16_f32 v170, v46, v47
	v_cvt_pk_bf16_f32 v171, v48, v49
	v_subrev_u32_e32 v234, s24, v146
	v_lshrrev_b32_e32 v235, 13, v234
	v_and_b32_e32 v236, 0x7f, v234
	v_bfe_u32 v237, v234, 7, 4
	v_bfe_u32 v238, v234, 12, 1
	v_lshrrev_b32_e32 v239, 13, v235
	v_lshl_add_u32 v239, v239, 4, v237
	v_bfe_u32 v237, v235, 6, 7
	v_lshl_add_u32 v239, v239, 7, v237
	v_lshl_add_u32 v239, v238, 13, v239
	v_bfe_u32 v237, v235, 5, 1
	v_lshl_add_u32 v239, v239, 1, v237
	v_and_b32_e32 v237, 31, v235
	v_lshl_add_u32 v236, v237, 7, v236
	v_lshl_add_u32 v236, v239, 13, v236
	v_add_u32_e32 v236, 0x800, v236
	v_mov_b32_e32 v237, 0
	v_lshl_add_u64 v[236:237], s[24:25], 0, v[236:237]
	global_store_dwordx4 v[236:237], v[168:171], off
	s_nop 1
	v_cvt_pk_bf16_f32 v168, v34, v35
	v_cvt_pk_bf16_f32 v169, v36, v37
	v_cvt_pk_bf16_f32 v170, v26, v27
	v_cvt_pk_bf16_f32 v171, v28, v29
	v_subrev_u32_e32 v234, s24, v146
	v_add_u32_e32 v234, 0x100, v234
	v_lshrrev_b32_e32 v235, 13, v234
	v_and_b32_e32 v236, 0x7f, v234
	v_bfe_u32 v237, v234, 7, 4
	v_bfe_u32 v238, v234, 12, 1
	v_lshrrev_b32_e32 v239, 13, v235
	v_lshl_add_u32 v239, v239, 4, v237
	v_bfe_u32 v237, v235, 6, 7
	v_lshl_add_u32 v239, v239, 7, v237
	v_lshl_add_u32 v239, v238, 13, v239
	v_bfe_u32 v237, v235, 5, 1
	v_lshl_add_u32 v239, v239, 1, v237
	v_and_b32_e32 v237, 31, v235
	v_lshl_add_u32 v236, v237, 7, v236
	v_lshl_add_u32 v236, v239, 13, v236
	v_add_u32_e32 v236, 0x800, v236
	v_mov_b32_e32 v237, 0
	v_lshl_add_u64 v[236:237], s[24:25], 0, v[236:237]
	global_store_dwordx4 v[236:237], v[168:171], off
	v_add_u32_e32 v146, 0xa0, v136
	v_ashrrev_i32_e32 v147, 31, v146
	v_lshlrev_b64 v[146:147], s63, v[146:147]
	v_lshl_add_u64 v[146:147], v[146:147], 1, s[24:25]
	v_lshl_add_u64 v[146:147], v[146:147], 0, v[134:135]
	v_cvt_pk_bf16_f32 v168, v38, v39
	v_cvt_pk_bf16_f32 v169, v40, v41
	v_cvt_pk_bf16_f32 v170, v30, v31
	v_cvt_pk_bf16_f32 v171, v32, v33
	v_subrev_u32_e32 v234, s24, v146
	v_lshrrev_b32_e32 v235, 13, v234
	v_and_b32_e32 v236, 0x7f, v234
	v_bfe_u32 v237, v234, 7, 4
	v_bfe_u32 v238, v234, 12, 1
	v_lshrrev_b32_e32 v239, 13, v235
	v_lshl_add_u32 v239, v239, 4, v237
	v_bfe_u32 v237, v235, 6, 7
	v_lshl_add_u32 v239, v239, 7, v237
	v_lshl_add_u32 v239, v238, 13, v239
	v_bfe_u32 v237, v235, 5, 1
	v_lshl_add_u32 v239, v239, 1, v237
	v_and_b32_e32 v237, 31, v235
	v_lshl_add_u32 v236, v237, 7, v236
	v_lshl_add_u32 v236, v239, 13, v236
	v_add_u32_e32 v236, 0x800, v236
	v_mov_b32_e32 v237, 0
	v_lshl_add_u64 v[236:237], s[24:25], 0, v[236:237]
	global_store_dwordx4 v[236:237], v[168:171], off
	s_nop 1
	v_cvt_pk_bf16_f32 v168, v18, v19
	v_cvt_pk_bf16_f32 v169, v20, v21
	v_cvt_pk_bf16_f32 v170, v10, v11
	v_cvt_pk_bf16_f32 v171, v12, v13
	v_subrev_u32_e32 v234, s24, v146
	v_add_u32_e32 v234, 0x100, v234
	v_lshrrev_b32_e32 v235, 13, v234
	v_and_b32_e32 v236, 0x7f, v234
	v_bfe_u32 v237, v234, 7, 4
	v_bfe_u32 v238, v234, 12, 1
	v_lshrrev_b32_e32 v239, 13, v235
	v_lshl_add_u32 v239, v239, 4, v237
	v_bfe_u32 v237, v235, 6, 7
	v_lshl_add_u32 v239, v239, 7, v237
	v_lshl_add_u32 v239, v238, 13, v239
	v_bfe_u32 v237, v235, 5, 1
	v_lshl_add_u32 v239, v239, 1, v237
	v_and_b32_e32 v237, 31, v235
	v_lshl_add_u32 v236, v237, 7, v236
	v_lshl_add_u32 v236, v239, 13, v236
	v_add_u32_e32 v236, 0x800, v236
	v_mov_b32_e32 v237, 0
	v_lshl_add_u64 v[236:237], s[24:25], 0, v[236:237]
	global_store_dwordx4 v[236:237], v[168:171], off
	v_add_u32_e32 v146, 0xb0, v136
	v_ashrrev_i32_e32 v147, 31, v146
	v_lshlrev_b64 v[146:147], s63, v[146:147]
	v_lshl_add_u64 v[146:147], v[146:147], 1, s[24:25]
	v_lshl_add_u64 v[158:159], v[146:147], 0, v[134:135]
	v_cvt_pk_bf16_f32 v168, v22, v23
	v_cvt_pk_bf16_f32 v169, v24, v25
	v_cvt_pk_bf16_f32 v170, v14, v15
	v_cvt_pk_bf16_f32 v171, v16, v17
	v_subrev_u32_e32 v234, s24, v158
	v_lshrrev_b32_e32 v235, 13, v234
	v_and_b32_e32 v236, 0x7f, v234
	v_bfe_u32 v237, v234, 7, 4
	v_bfe_u32 v238, v234, 12, 1
	v_lshrrev_b32_e32 v239, 13, v235
	v_lshl_add_u32 v239, v239, 4, v237
	v_bfe_u32 v237, v235, 6, 7
	v_lshl_add_u32 v239, v239, 7, v237
	v_lshl_add_u32 v239, v238, 13, v239
	v_bfe_u32 v237, v235, 5, 1
	v_lshl_add_u32 v239, v239, 1, v237
	v_and_b32_e32 v237, 31, v235
	v_lshl_add_u32 v236, v237, 7, v236
	v_lshl_add_u32 v236, v239, 13, v236
	v_add_u32_e32 v236, 0x800, v236
	v_mov_b32_e32 v237, 0
	v_lshl_add_u64 v[236:237], s[24:25], 0, v[236:237]
	global_store_dwordx4 v[236:237], v[168:171], off
	s_branch .LBB0_133

; __device__ __forceinline__ unsigned cvt_pk_bf16(float lo, float hi) { f32x2_t v = {lo, hi}; bf16x2_t b = __builtin_convertvector(v, bf16x2_t); return __builtin_bit_cast(unsigned, b); }
; __device__ __forceinline__ float bf_lo(unsigned w) { return __uint_as_float(w << 16); }
; __device__ __forceinline__ float bf_hi(unsigned w) { return __uint_as_float(w & 0xffff0000u); }
; __device__ __forceinline__ float silu_f(float z) { return z * __builtin_amdgcn_rcpf(1.0f + fast_exp2(-1.4426950408889634f * z)); }
; __device__ __forceinline__ void sb_unit(LAS unsigned char* lds, const bf16_t* __restrict__ u, bf16_t* __restrict__ yz, int b, int h, int qb) {
;     ...
;     { const bf16_t* zp = u + (rowbase + t_row) * NIN + 3 * DM + h * 64 + 4 * hi;
;       bf16_t* yp = yz + (rowbase + t_row) * DM + h * 64 + 4 * hi;
; #pragma unroll
;       for (int c = 0; c < 2; ++c)
; #pragma unroll
;         for (int g = 0; g < 4; ++g) { const u32x2 zz = *(const u32x2*)(zp + 32 * c + 8 * g);
;             const float a0 = (c ? o1 : o0)[4 * g + 0] * silu_f(bf_lo(zz.x)), a1 = (c ? o1 : o0)[4 * g + 1] * silu_f(bf_hi(zz.x));
;             const float a2 = (c ? o1 : o0)[4 * g + 2] * silu_f(bf_lo(zz.y)), a3 = (c ? o1 : o0)[4 * g + 3] * silu_f(bf_hi(zz.y));
;             u32x2 w; w.x = cvt_pk_bf16(a0, a1); w.y = cvt_pk_bf16(a2, a3); *(u32x2*)(yp + 32 * c + 8 * g) = w; } }
.LBB0_297:
	s_lshl_b32 s96, s16, 1
	v_lshl_add_u64 v[34:35], v[84:85], 0, s[96:97]
	v_mov_b32_e32 v87, v1
	v_lshl_add_u64 v[38:39], v[34:35], 0, v[86:87]
	s_mov_b64 s[4:5], 0x1800
	v_lshl_add_u64 v[36:37], v[38:39], 0, s[4:5]
	v_add_co_u32_e32 v38, vcc, 0x1000, v38
	v_readlane_b32 s4, v233, 39
	s_nop 0
	v_addc_co_u32_e32 v39, vcc, 0, v39, vcc
	v_lshlrev_b64 v[34:35], 11, v[82:83]
	v_readlane_b32 s5, v233, 40
	s_add_i32 s14, s14, s38
	s_add_i32 s3, s3, s38
	v_lshl_add_u64 v[34:35], s[4:5], 0, v[34:35]
	v_lshl_add_u64 v[34:35], v[34:35], 0, s[96:97]
	v_lshl_add_u64 v[34:35], v[34:35], 0, v[86:87]
	s_cmpk_gt_i32 s14, 0x7ff
	s_waitcnt vmcnt(0)
	v_lshrrev_b32_e32 v150, 5, v162
	v_lshlrev_b32_e32 v150, 3, v150
	v_mov_b32_e32 v151, 0
	v_lshl_add_u64 v[150:151], v[34:35], 0, v[150:151]
	v_lshlrev_b32_e32 v104, 16, v208
	v_and_b32_e32 v105, 0xffff0000, v208
	v_lshlrev_b32_e32 v106, 16, v209
	v_and_b32_e32 v107, 0xffff0000, v209
	v_lshlrev_b32_e32 v142, 16, v210
	v_and_b32_e32 v143, 0xffff0000, v210
	v_lshlrev_b32_e32 v144, 16, v211
	v_and_b32_e32 v145, 0xffff0000, v211
	v_mul_f32_e32 v108, 0xbfb8aa3b, v104
	v_mul_f32_e32 v109, 0xbfb8aa3b, v105
	v_mul_f32_e32 v110, 0xbfb8aa3b, v106
	v_mul_f32_e32 v111, 0xbfb8aa3b, v107
	v_mul_f32_e32 v146, 0xbfb8aa3b, v142
	v_mul_f32_e32 v147, 0xbfb8aa3b, v143
	v_mul_f32_e32 v148, 0xbfb8aa3b, v144
	v_mul_f32_e32 v149, 0xbfb8aa3b, v145
	v_exp_f32_e32 v108, v108
	v_exp_f32_e32 v109, v109
	v_exp_f32_e32 v110, v110
	v_exp_f32_e32 v111, v111
	v_exp_f32_e32 v146, v146
	v_exp_f32_e32 v147, v147
	v_exp_f32_e32 v148, v148
	v_exp_f32_e32 v149, v149
	v_add_f32_e32 v108, 1.0, v108
	v_add_f32_e32 v109, 1.0, v109
	v_add_f32_e32 v110, 1.0, v110
	v_add_f32_e32 v111, 1.0, v111
	v_add_f32_e32 v146, 1.0, v146
	v_add_f32_e32 v147, 1.0, v147
	v_add_f32_e32 v148, 1.0, v148
	v_add_f32_e32 v149, 1.0, v149
	v_rcp_f32_e32 v108, v108
	v_rcp_f32_e32 v109, v109
	v_rcp_f32_e32 v110, v110
	v_rcp_f32_e32 v111, v111
	v_rcp_f32_e32 v146, v146
	v_rcp_f32_e32 v147, v147
	v_rcp_f32_e32 v148, v148
	v_rcp_f32_e32 v149, v149
	v_mul_f32_e32 v104, v108, v104
	v_mul_f32_e32 v105, v109, v105
	v_mul_f32_e32 v106, v110, v106
	v_mul_f32_e32 v107, v111, v107
	v_mul_f32_e32 v142, v146, v142
	v_mul_f32_e32 v143, v147, v143
	v_mul_f32_e32 v144, v148, v144
	v_mul_f32_e32 v145, v149, v145
	v_mul_f32_e32 v104, v18, v104
	v_mul_f32_e32 v105, v19, v105
	v_mul_f32_e32 v106, v20, v106
	v_mul_f32_e32 v107, v21, v107
	v_mul_f32_e32 v142, v22, v142
	v_mul_f32_e32 v143, v23, v143
	v_mul_f32_e32 v144, v24, v144
	v_mul_f32_e32 v145, v25, v145
	v_cvt_pk_bf16_f32 v88, v104, v105
	v_cvt_pk_bf16_f32 v89, v106, v107
	v_cvt_pk_bf16_f32 v90, v142, v143
	v_cvt_pk_bf16_f32 v91, v144, v145
	s_nop 1
	v_permlane32_swap_b32_e32 v88, v90
	v_permlane32_swap_b32_e32 v89, v91
	global_store_dwordx4 v[150:151], v[88:91], off
	v_lshlrev_b32_e32 v104, 16, v212
	v_and_b32_e32 v105, 0xffff0000, v212
	v_lshlrev_b32_e32 v106, 16, v213
	v_and_b32_e32 v107, 0xffff0000, v213
	v_lshlrev_b32_e32 v142, 16, v214
	v_and_b32_e32 v143, 0xffff0000, v214
	v_lshlrev_b32_e32 v144, 16, v215
	v_and_b32_e32 v145, 0xffff0000, v215
	v_mul_f32_e32 v108, 0xbfb8aa3b, v104
	v_mul_f32_e32 v109, 0xbfb8aa3b, v105
	v_mul_f32_e32 v110, 0xbfb8aa3b, v106
	v_mul_f32_e32 v111, 0xbfb8aa3b, v107
	v_mul_f32_e32 v146, 0xbfb8aa3b, v142
	v_mul_f32_e32 v147, 0xbfb8aa3b, v143
	v_mul_f32_e32 v148, 0xbfb8aa3b, v144
	v_mul_f32_e32 v149, 0xbfb8aa3b, v145
	v_exp_f32_e32 v108, v108
	v_exp_f32_e32 v109, v109
	v_exp_f32_e32 v110, v110
	v_exp_f32_e32 v111, v111
	v_exp_f32_e32 v146, v146
	v_exp_f32_e32 v147, v147
	v_exp_f32_e32 v148, v148
	v_exp_f32_e32 v149, v149
	v_add_f32_e32 v108, 1.0, v108
	v_add_f32_e32 v109, 1.0, v109
	v_add_f32_e32 v110, 1.0, v110
	v_add_f32_e32 v111, 1.0, v111
	v_add_f32_e32 v146, 1.0, v146
	v_add_f32_e32 v147, 1.0, v147
	v_add_f32_e32 v148, 1.0, v148
	v_add_f32_e32 v149, 1.0, v149
	v_rcp_f32_e32 v108, v108
	v_rcp_f32_e32 v109, v109
	v_rcp_f32_e32 v110, v110
	v_rcp_f32_e32 v111, v111
	v_rcp_f32_e32 v146, v146
	v_rcp_f32_e32 v147, v147
	v_rcp_f32_e32 v148, v148
	v_rcp_f32_e32 v149, v149
	v_mul_f32_e32 v104, v108, v104
	v_mul_f32_e32 v105, v109, v105
	v_mul_f32_e32 v106, v110, v106
	v_mul_f32_e32 v107, v111, v107
	v_mul_f32_e32 v142, v146, v142
	v_mul_f32_e32 v143, v147, v143
	v_mul_f32_e32 v144, v148, v144
	v_mul_f32_e32 v145, v149, v145
	v_mul_f32_e32 v104, v26, v104
	v_mul_f32_e32 v105, v27, v105
	v_mul_f32_e32 v106, v28, v106
	v_mul_f32_e32 v107, v29, v107
	v_mul_f32_e32 v142, v30, v142
	v_mul_f32_e32 v143, v31, v143
	v_mul_f32_e32 v144, v32, v144
	v_mul_f32_e32 v145, v33, v145
	v_cvt_pk_bf16_f32 v92, v104, v105
	v_cvt_pk_bf16_f32 v93, v106, v107
	v_cvt_pk_bf16_f32 v94, v142, v143
	v_cvt_pk_bf16_f32 v95, v144, v145
	s_nop 1
	v_permlane32_swap_b32_e32 v92, v94
	v_permlane32_swap_b32_e32 v93, v95
	global_store_dwordx4 v[150:151], v[92:95], off offset:32
	v_lshlrev_b32_e32 v104, 16, v216
	v_and_b32_e32 v105, 0xffff0000, v216
	v_lshlrev_b32_e32 v106, 16, v217
	v_and_b32_e32 v107, 0xffff0000, v217
	v_lshlrev_b32_e32 v142, 16, v218
	v_and_b32_e32 v143, 0xffff0000, v218
	v_lshlrev_b32_e32 v144, 16, v219
	v_and_b32_e32 v145, 0xffff0000, v219
	v_mul_f32_e32 v108, 0xbfb8aa3b, v104
	v_mul_f32_e32 v109, 0xbfb8aa3b, v105
	v_mul_f32_e32 v110, 0xbfb8aa3b, v106
	v_mul_f32_e32 v111, 0xbfb8aa3b, v107
	v_mul_f32_e32 v146, 0xbfb8aa3b, v142
	v_mul_f32_e32 v147, 0xbfb8aa3b, v143
	v_mul_f32_e32 v148, 0xbfb8aa3b, v144
	v_mul_f32_e32 v149, 0xbfb8aa3b, v145
	v_exp_f32_e32 v108, v108
	v_exp_f32_e32 v109, v109
	v_exp_f32_e32 v110, v110
	v_exp_f32_e32 v111, v111
	v_exp_f32_e32 v146, v146
	v_exp_f32_e32 v147, v147
	v_exp_f32_e32 v148, v148
; __device__ __forceinline__ unsigned cvt_pk_bf16(float lo, float hi) { f32x2_t v = {lo, hi}; bf16x2_t b = __builtin_convertvector(v, bf16x2_t); return __builtin_bit_cast(unsigned, b); }
; __device__ __forceinline__ float bf_lo(unsigned w) { return __uint_as_float(w << 16); }
; __device__ __forceinline__ float bf_hi(unsigned w) { return __uint_as_float(w & 0xffff0000u); }
; __device__ __forceinline__ float silu_f(float z) { return z * __builtin_amdgcn_rcpf(1.0f + fast_exp2(-1.4426950408889634f * z)); }
; __device__ __forceinline__ void sb_unit(LAS unsigned char* lds, const bf16_t* __restrict__ u, bf16_t* __restrict__ yz, int b, int h, int qb) {
;     ...
;         for (int g = 0; g < 4; ++g) { const u32x2 zz = *(const u32x2*)(zp + 32 * c + 8 * g);
;             const float a0 = (c ? o1 : o0)[4 * g + 0] * silu_f(bf_lo(zz.x)), a1 = (c ? o1 : o0)[4 * g + 1] * silu_f(bf_hi(zz.x));
;             const float a2 = (c ? o1 : o0)[4 * g + 2] * silu_f(bf_lo(zz.y)), a3 = (c ? o1 : o0)[4 * g + 3] * silu_f(bf_hi(zz.y));
;             u32x2 w; w.x = cvt_pk_bf16(a0, a1); w.y = cvt_pk_bf16(a2, a3); *(u32x2*)(yp + 32 * c + 8 * g) = w; } }
	v_exp_f32_e32 v149, v149
	v_add_f32_e32 v108, 1.0, v108
	v_add_f32_e32 v109, 1.0, v109
	v_add_f32_e32 v110, 1.0, v110
	v_add_f32_e32 v111, 1.0, v111
	v_add_f32_e32 v146, 1.0, v146
	v_add_f32_e32 v147, 1.0, v147
	v_add_f32_e32 v148, 1.0, v148
	v_add_f32_e32 v149, 1.0, v149
	v_rcp_f32_e32 v108, v108
	v_rcp_f32_e32 v109, v109
	v_rcp_f32_e32 v110, v110
	v_rcp_f32_e32 v111, v111
	v_rcp_f32_e32 v146, v146
	v_rcp_f32_e32 v147, v147
	v_rcp_f32_e32 v148, v148
	v_rcp_f32_e32 v149, v149
	v_mul_f32_e32 v104, v108, v104
	v_mul_f32_e32 v105, v109, v105
	v_mul_f32_e32 v106, v110, v106
	v_mul_f32_e32 v107, v111, v107
	v_mul_f32_e32 v142, v146, v142
	v_mul_f32_e32 v143, v147, v143
	v_mul_f32_e32 v144, v148, v144
	v_mul_f32_e32 v145, v149, v145
	v_mul_f32_e32 v104, v2, v104
	v_mul_f32_e32 v105, v3, v105
	v_mul_f32_e32 v106, v4, v106
	v_mul_f32_e32 v107, v5, v107
	v_mul_f32_e32 v142, v6, v142
	v_mul_f32_e32 v143, v7, v143
	v_mul_f32_e32 v144, v8, v144
	v_mul_f32_e32 v145, v9, v145
	v_cvt_pk_bf16_f32 v96, v104, v105
	v_cvt_pk_bf16_f32 v97, v106, v107
	v_cvt_pk_bf16_f32 v98, v142, v143
	v_cvt_pk_bf16_f32 v99, v144, v145
	s_nop 1
	v_permlane32_swap_b32_e32 v96, v98
	v_permlane32_swap_b32_e32 v97, v99
	global_store_dwordx4 v[150:151], v[96:99], off offset:64
	v_lshlrev_b32_e32 v104, 16, v220
	v_and_b32_e32 v105, 0xffff0000, v220
	v_lshlrev_b32_e32 v106, 16, v221
	v_and_b32_e32 v107, 0xffff0000, v221
	v_lshlrev_b32_e32 v142, 16, v222
	v_and_b32_e32 v143, 0xffff0000, v222
	v_lshlrev_b32_e32 v144, 16, v223
	v_and_b32_e32 v145, 0xffff0000, v223
	v_mul_f32_e32 v108, 0xbfb8aa3b, v104
	v_mul_f32_e32 v109, 0xbfb8aa3b, v105
	v_mul_f32_e32 v110, 0xbfb8aa3b, v106
	v_mul_f32_e32 v111, 0xbfb8aa3b, v107
	v_mul_f32_e32 v146, 0xbfb8aa3b, v142
	v_mul_f32_e32 v147, 0xbfb8aa3b, v143
	v_mul_f32_e32 v148, 0xbfb8aa3b, v144
	v_mul_f32_e32 v149, 0xbfb8aa3b, v145
	v_exp_f32_e32 v108, v108
	v_exp_f32_e32 v109, v109
	v_exp_f32_e32 v110, v110
	v_exp_f32_e32 v111, v111
	v_exp_f32_e32 v146, v146
	v_exp_f32_e32 v147, v147
	v_exp_f32_e32 v148, v148
	v_exp_f32_e32 v149, v149
	v_add_f32_e32 v108, 1.0, v108
	v_add_f32_e32 v109, 1.0, v109
	v_add_f32_e32 v110, 1.0, v110
	v_add_f32_e32 v111, 1.0, v111
	v_add_f32_e32 v146, 1.0, v146
	v_add_f32_e32 v147, 1.0, v147
	v_add_f32_e32 v148, 1.0, v148
	v_add_f32_e32 v149, 1.0, v149
	v_rcp_f32_e32 v108, v108
	v_rcp_f32_e32 v109, v109
	v_rcp_f32_e32 v110, v110
	v_rcp_f32_e32 v111, v111
	v_rcp_f32_e32 v146, v146
	v_rcp_f32_e32 v147, v147
	v_rcp_f32_e32 v148, v148
	v_rcp_f32_e32 v149, v149
	v_mul_f32_e32 v104, v108, v104
	v_mul_f32_e32 v105, v109, v105
	v_mul_f32_e32 v106, v110, v106
	v_mul_f32_e32 v107, v111, v107
	v_mul_f32_e32 v142, v146, v142
	v_mul_f32_e32 v143, v147, v143
	v_mul_f32_e32 v144, v148, v144
	v_mul_f32_e32 v145, v149, v145
	v_mul_f32_e32 v104, v10, v104
	v_mul_f32_e32 v105, v11, v105
	v_mul_f32_e32 v106, v12, v106
	v_mul_f32_e32 v107, v13, v107
	v_mul_f32_e32 v142, v14, v142
	v_mul_f32_e32 v143, v15, v143
	v_mul_f32_e32 v144, v16, v144
	v_mul_f32_e32 v145, v17, v145
	v_cvt_pk_bf16_f32 v100, v104, v105
	v_cvt_pk_bf16_f32 v101, v106, v107
	v_cvt_pk_bf16_f32 v102, v142, v143
	v_cvt_pk_bf16_f32 v103, v144, v145
	s_nop 1
	v_permlane32_swap_b32_e32 v100, v102
	v_permlane32_swap_b32_e32 v101, v103
	global_store_dwordx4 v[150:151], v[100:103], off offset:96
	s_cbranch_scc1 .LBB0_293
; #define LAS __attribute__((address_space(3)))
; __device__ __forceinline__ int swap23(int i) { return (i & ~12) | ((i & 4) << 1) | ((i & 8) >> 1); }
; __device__ __forceinline__ void sb_unit(LAS unsigned char* lds, const bf16_t* __restrict__ u, bf16_t* __restrict__ yz, int b, int h, int qb) {
;     ...
;     const int tid = tid_, lane = tid & 63, wid = __builtin_amdgcn_readfirstlane(tid >> 6), q31 = lane & 31, hi = lane >> 5;
;     const size_t rowbase = (size_t)b * SEQ;
;     const int q0 = qb * 256, tw = q0 + 32 * wid, t_row = tw + q31;
;     const int kt_top = qb * 4 + 3;
;     const unsigned lds0 = (unsigned)(uintptr_t)lds;
;     const int rho = 8 * wid + (lane >> 3);
;     const unsigned koff = (unsigned)((((rho & 32) | swap23(rho & 31)) * NIN + (((lane & 7) ^ ((rho >> 1) & 7)) * 8)) * 2);
;     const int fr_ = (rho & 3) | ((((rho >> 1) ^ (rho >> 2)) & 1) << 2);
;     const unsigned voff = (unsigned)((rho * NIN + (((lane & 7) ^ fr_) * 8)) * 2);
;     const char* kgb = (const char*)(u + rowbase * NIN + DM + h * 64);
;     const char* vgb = (const char*)(u + rowbase * NIN + 2 * DM + h * 64);
;     bf16x8 qf[4];
;     { const bf16_t* qp = u + (rowbase + t_row) * NIN + h * 64 + hi * 8;
; #pragma unroll
;       for (int d0 = 0; d0 < 4; ++d0) qf[d0] = *(const bf16x8*)(qp + 16 * d0); }
;     unsigned kfa[4];
; #pragma unroll
;     for (int d0 = 0; d0 < 4; ++d0) kfa[d0] = q31 * 128 + (((2 * d0 + hi) ^ ((q31 >> 1) & 7)) << 4);
;     const int blk = (lane >> 4) & 1, qq = (lane & 15) >> 2, pp = lane & 3, bq = (qq >> 1) & 1, jx = (2 * blk + (pp >> 1)) ^ qq;
;     unsigned vra[2][2];
; #pragma unroll
;     for (int c = 0; c < 2; ++c)
; #pragma unroll
;         for (int t = 0; t < 2; ++t) vra[c][t] = 8192 + (8 * hi + 4 * t + qq) * 128 + ((4 * (c ^ bq ^ t) + jx) << 4) + 8 * (pp & 1);
;     LAS unsigned* flags = (LAS unsigned*)(lds + 131072 + 128);
;     float carry = 0.f; bool done = false;
;     f32x16 o0, o1, zero16;
; #pragma unroll
;     for (int r = 0; r < 16; ++r) { o0[r] = 0.f; o1[r] = 0.f; zero16[r] = 0.f; }
;     ...
;     { const bf16_t* zp = u + (rowbase + t_row) * NIN + 3 * DM + h * 64 + 4 * hi;
;       bf16_t* yp = yz + (rowbase + t_row) * DM + h * 64 + 4 * hi;
; #pragma unroll
;       for (int c = 0; c < 2; ++c)
; #pragma unroll
;         for (int g = 0; g < 4; ++g) { const u32x2 zz = *(const u32x2*)(zp + 32 * c + 8 * g);
.LBB0_298:
	v_mov_b32_e32 v4, v140
	s_and_b32 s8, s14, 31
	v_readfirstlane_b32 s5, v4
	s_ashr_i32 s9, s5, 6
	s_and_b32 s2, s3, 31
	s_ashr_i32 s4, s14, 9
	s_lshl_b32 s10, s8, 8
	s_lshl_b32 s11, s9, 5
	s_lshl_b32 s2, s2, 8
	v_and_b32_e32 v6, 31, v4
	s_ashr_i32 s5, s4, 31
	s_add_i32 s15, s11, s10
	s_lshl_b32 s10, s9, 3
	v_bfe_u32 v0, v4, 3, 3
	v_lshrrev_b32_e32 v3, 2, v4
	s_lshl_b32 s12, s9, 2
	s_addk_i32 s2, 0x100
	s_lshl_b64 s[6:7], s[4:5], 13
	v_or_b32_e32 v2, s15, v6
	s_lshl_b32 s8, s8, 2
	v_or_b32_e32 v8, s10, v0
	v_and_b32_e32 v3, 8, v3
	s_and_b32 s13, s12, 4
	v_bitop3_b32 v0, s10, 51, v0 bitop3:0xc8
	s_lshl_b64 s[4:5], s[4:5], 26
	v_or3_b32 v9, v0, s13, v3
	s_add_u32 s4, s34, s4
	v_ashrrev_i32_e32 v3, 31, v2
	v_ashrrev_i32_e32 v11, 1, v8
	s_addc_u32 s5, s35, s5
	s_lshl_b32 s10, s14, 1
	v_lshl_add_u64 v[82:83], s[6:7], 0, v[2:3]
	v_xor_b32_e32 v0, v11, v4
	s_and_b32 s16, s10, 0x3c0
	v_lshlrev_b64 v[2:3], 13, v[82:83]
	v_bfe_u32 v7, v4, 5, 1
	v_lshlrev_b32_e32 v0, 4, v0
	v_lshl_add_u64 v[84:85], s[34:35], 0, v[2:3]
	s_lshl_b32 s96, s16, 1
	v_and_b32_e32 v12, 0x70, v0
	v_lshl_add_u64 v[2:3], v[84:85], 0, s[96:97]
	v_lshlrev_b32_e32 v0, 4, v7
	v_lshl_add_u64 v[2:3], v[2:3], 0, v[0:1]
	global_load_dwordx4 v[66:69], v[2:3], off
	global_load_dwordx4 v[70:73], v[2:3], off offset:32
	global_load_dwordx4 v[74:77], v[2:3], off offset:64
	global_load_dwordx4 v[78:81], v[2:3], off offset:96
	v_lshrrev_b32_e32 v0, 5, v4
	v_xor_b32_e32 v0, v11, v0
	v_and_b32_e32 v5, 63, v4
	v_lshlrev_b32_e32 v0, 2, v0
	v_and_b32_e32 v10, 7, v4
	v_bfe_u32 v13, v5, 3, 2
	v_and_b32_e32 v0, 4, v0
	s_add_u32 s4, s4, s96
	v_bitop3_b32 v0, v0, v10, v13 bitop3:0x36
	v_lshlrev_b32_e32 v2, 13, v8
	s_addc_u32 s5, s5, 0
	s_add_u32 s17, s4, 0x800
	v_lshl_or_b32 v87, v0, 4, v2
	v_lshrrev_b32_e32 v2, 3, v4
	s_addc_u32 s18, s5, 0
	s_or_b32 s19, s8, 3
	v_bfe_u32 v0, v4, 2, 2
	v_and_b32_e32 v2, 2, v2
	v_bfe_u32 v14, v4, 1, 1
	v_lshrrev_b32_e32 v8, 1, v4
	v_bfe_u32 v10, v4, 1, 3
	v_bitop3_b32 v2, v2, v0, v14 bitop3:0x36
	v_lshlrev_b32_e32 v4, 3, v4
	s_add_u32 s20, s4, 0x1000
	v_lshlrev_b32_e32 v2, 4, v2
	v_and_b32_e32 v14, 8, v4
	v_and_b32_e32 v4, 64, v4
	s_addc_u32 s21, s5, 0
	s_lshl_b32 s4, s9, 10
	v_or_b32_e32 v15, v2, v4
	s_add_i32 s22, s4, 0
	v_cmp_gt_u32_e64 s[4:5], 32, v5
	v_cmp_eq_u32_e64 s[6:7], 0, v5
	v_lshlrev_b32_e32 v5, 10, v7
	v_lshlrev_b32_e32 v86, 3, v7
	v_bitop3_b32 v8, v7, v8, 7 bitop3:0x78
	v_bitop3_b32 v11, v7, v10, 2 bitop3:0x36
	v_bitop3_b32 v13, v7, v10, 4 bitop3:0x36
	v_bitop3_b32 v10, v7, v10, 6 bitop3:0x36
	v_bitop3_b32 v7, v15, v5, 64 bitop3:0xde
	v_lshlrev_b32_e32 v0, 7, v0
	v_add_u32_e32 v7, v7, v0
	v_or3_b32 v0, v5, v0, v4
	v_lshlrev_b32_e32 v3, 7, v6
	v_or3_b32 v0, v0, v2, v14
	v_add_u32_e32 v170, 0, v0
	v_lshl_or_b32 v0, v10, 4, v3
	v_add_u32_e32 v171, 0, v0
	v_lshl_or_b32 v0, v13, 4, v3
	v_add_u32_e32 v172, 0, v0
	v_lshl_or_b32 v0, v11, 4, v3
	v_add_u32_e32 v173, 0, v0
	v_lshl_or_b32 v0, v8, 4, v3
	s_addk_i32 s11, 0xff40
	v_or_b32_e32 v7, v7, v14
	v_add_u32_e32 v174, 0, v0
	v_or_b32_e32 v0, s11, v6
	v_mov_b32_e32 v14, v1
	v_mov_b32_e32 v15, v1
	v_lshl_or_b32 v168, v9, 13, v12
	v_add_u32_e32 v169, 0, v7
	v_sub_u32_e32 v175, v0, v86
	v_mov_b32_e32 v0, v1
	v_mov_b32_e32 v2, v1
	v_mov_b32_e32 v3, v1
	v_mov_b32_e32 v4, v1
	v_mov_b32_e32 v5, v1
	v_mov_b32_e32 v6, v1
	v_mov_b32_e32 v7, v1
	v_mov_b32_e32 v8, v1
	v_mov_b32_e32 v9, v1
	v_mov_b32_e32 v10, v1
	v_mov_b32_e32 v11, v1
	v_mov_b32_e32 v12, v1
	v_mov_b32_e32 v13, v1
	v_mov_b64_e32 v[32:33], v[14:15]
	s_add_i32 s23, s12, 0
	v_mov_b64_e32 v[30:31], v[12:13]
	v_mov_b64_e32 v[28:29], v[10:11]
	v_mov_b64_e32 v[26:27], v[8:9]
	v_mov_b64_e32 v[24:25], v[6:7]
	v_mov_b64_e32 v[22:23], v[4:5]
	v_mov_b64_e32 v[20:21], v[2:3]
	v_mov_b64_e32 v[18:19], v[0:1]
	v_mov_b64_e32 v[16:17], v[14:15]
	s_add_i32 s23, s23, 0x20080
	v_mov_b32_e32 v176, 0
	s_mov_b64 s[8:9], 0
	v_mov_b64_e32 v[14:15], v[12:13]
	v_mov_b64_e32 v[12:13], v[10:11]
	v_mov_b64_e32 v[10:11], v[8:9]
	v_mov_b64_e32 v[8:9], v[6:7]
	v_mov_b64_e32 v[6:7], v[4:5]
	v_mov_b64_e32 v[4:5], v[2:3]
	v_mov_b64_e32 v[2:3], v[0:1]
	v_mov_b32_e32 v224, v86
	v_mov_b32_e32 v225, 0
	v_lshl_add_u64 v[224:225], v[84:85], 0, v[224:225]
	v_lshl_add_u64 v[224:225], v[224:225], 0, s[96:97]
	s_mov_b64 s[10:11], 0x1800
	v_lshl_add_u64 v[224:225], v[224:225], 0, s[10:11]
	global_load_dwordx2 v[208:209], v[224:225], off
	global_load_dwordx2 v[210:211], v[224:225], off offset:16
	global_load_dwordx2 v[212:213], v[224:225], off offset:32
	global_load_dwordx2 v[214:215], v[224:225], off offset:48
	global_load_dwordx2 v[216:217], v[224:225], off offset:64
	global_load_dwordx2 v[218:219], v[224:225], off offset:80
	global_load_dwordx2 v[220:221], v[224:225], off offset:96
	global_load_dwordx2 v[222:223], v[224:225], off offset:112
	s_lshr_b32 s10, s14, 5
	s_mov_b32 s11, 0
	s_lshl_b64 s[10:11], s[10:11], 21
	s_add_u32 s17, s34, s10
	s_addc_u32 s18, s35, s11
	s_add_u32 s20, s17, 0x8000000
	s_addc_u32 s21, s18, 0
	v_lshrrev_b32_e32 v204, 13, v168
	v_and_b32_e32 v205, 0x7f, v168
	v_and_b32_e32 v206, 31, v204
	v_lshrrev_b32_e32 v204, 5, v204
	v_lshlrev_b32_e32 v204, 13, v204
	v_lshl_add_u32 v204, v206, 7, v204
	v_add_u32_e32 v204, v204, v205
	v_add_u32_e32 v168, 0x800, v204
	v_lshrrev_b32_e32 v204, 13, v87
	v_and_b32_e32 v205, 0x7f, v87
	v_and_b32_e32 v206, 31, v204
	v_lshrrev_b32_e32 v204, 5, v204
	v_lshlrev_b32_e32 v204, 13, v204
	v_lshl_add_u32 v204, v206, 7, v204
	v_add_u32_e32 v204, v204, v205
	v_add_u32_e32 v87, 0x800, v204
	s_mov_b32 s96, s19
	s_branch .LBB0_300

; __device__ __forceinline__ void sb_unit(LAS unsigned char* lds, const bf16_t* __restrict__ u, bf16_t* __restrict__ yz, int b, int h, int qb) {
;     ...
;         for (int i = 0; i < 8; ++i) { const int kk = kt_hi - i;
;             if (kk >= 0) { const unsigned d_ = (unsigned)__builtin_amdgcn_readfirstlane(lds0 + i * 16384 + wid * 1024);
;                 glds16(kgb + (size_t)kk * (64 * NIN * 2), koff, d_); glds16(vgb + (size_t)kk * (64 * NIN * 2), voff, d_ + 8192); } }
.LBB0_302:
	s_andn2_b64 vcc, exec, s[10:11]
	s_cbranch_vccnz .LBB0_299
	s_lshl_b64 s[10:11], s[96:97], 14
	s_add_u32 s12, s20, s10
	s_addc_u32 s13, s21, s11
	s_add_u32 s10, s17, s10
	s_addc_u32 s11, s18, s11
	s_mov_b32 s24, m0
	s_mov_b32 m0, s22
	s_nop 0
	global_load_lds_dwordx4 v168, s[10:11]
	s_mov_b32 m0, s24
	s_add_i32 s10, s22, 0x2000
	s_mov_b32 s11, m0
	s_mov_b32 m0, s10
	s_nop 0
	global_load_lds_dwordx4 v87, s[12:13]
	s_mov_b32 m0, s11
	s_cmp_eq_u32 s96, 0
	s_cbranch_scc1 .LBB0_305
	s_add_i32 s10, s96, -1
	s_mov_b32 s11, s97
	s_lshl_b64 s[10:11], s[10:11], 14
	s_add_u32 s12, s20, s10
	s_addc_u32 s13, s21, s11
	s_add_u32 s10, s17, s10
	s_addc_u32 s11, s18, s11
	s_add_i32 s24, s22, 0x4000
	s_mov_b32 s25, m0
	s_mov_b32 m0, s24
	s_nop 0
	global_load_lds_dwordx4 v168, s[10:11]
	s_mov_b32 m0, s25
	s_add_i32 s10, s22, 0x6000
	s_mov_b32 s11, m0
	s_mov_b32 m0, s10
	s_nop 0
	global_load_lds_dwordx4 v87, s[12:13]
	s_mov_b32 m0, s11

; #define WAITV_BAR(N) asm volatile("s_waitcnt vmcnt(" #N ") lgkmcnt(0)\n\ts_barrier" ::: "memory")
; __device__ __forceinline__ void sb_unit(LAS unsigned char* lds, const bf16_t* __restrict__ u, bf16_t* __restrict__ yz, int b, int h, int qb) {
;     ...
;         for (int i = 0; i < 8; ++i) { const int kk = kt_hi - i;
;             if (kk >= 0) { const unsigned d_ = (unsigned)__builtin_amdgcn_readfirstlane(lds0 + i * 16384 + wid * 1024);
;                 glds16(kgb + (size_t)kk * (64 * NIN * 2), koff, d_); glds16(vgb + (size_t)kk * (64 * NIN * 2), voff, d_ + 8192); } }
;         WAITV_BAR(0);
.LBB0_311:
	s_add_i32 s10, s96, -7
	s_mov_b32 s11, s97
	s_lshl_b64 s[10:11], s[10:11], 14
	s_add_u32 s12, s20, s10
	s_addc_u32 s13, s21, s11
	s_add_u32 s10, s17, s10
	s_addc_u32 s11, s18, s11
	s_add_i32 s24, s22, 0x1c000
	s_mov_b32 s25, m0
	s_mov_b32 m0, s24
	s_nop 0
	global_load_lds_dwordx4 v168, s[10:11]
	s_mov_b32 m0, s25
	s_add_i32 s10, s22, 0x1e000
	s_mov_b32 s11, m0
	s_mov_b32 m0, s10
	s_nop 0
	global_load_lds_dwordx4 v87, s[12:13]
	s_mov_b32 m0, s11
.LBB0_312:
	s_cmp_lt_u32 s96, 7
	s_cbranch_scc1 .Lsb_short_round
	s_waitcnt vmcnt(8) lgkmcnt(0)
	s_branch .Lsb_stage1

; #define WAITV_BAR(N) asm volatile("s_waitcnt vmcnt(" #N ") lgkmcnt(0)\n\ts_barrier" ::: "memory")
; __device__ __forceinline__ void sb_unit(LAS unsigned char* lds, const bf16_t* __restrict__ u, bf16_t* __restrict__ yz, int b, int h, int qb) {
;     ...
;         WAITV_BAR(0);
;         if (!done) {
;             for (int i = 0; i < 8; ++i) { const int kt = kt_hi - i; if (kt < 0) { done = true; break; }
.Lsb_stage1:
	s_barrier
	v_writelane_b32 v232, 0, 61
	s_xor_b64 s[8:9], s[8:9], -1
	s_andn2_b64 vcc, exec, s[8:9]
	s_mov_b64 s[8:9], -1
	s_cbranch_vccnz .LBB0_325
	s_mov_b64 s[8:9], 0
	s_mov_b32 s24, 0
	s_mov_b32 s25, s96
	v_mov_b32_e32 v0, v175
	s_mov_b32 s27, s2
	s_branch .LBB0_315

; #define LAS __attribute__((address_space(3)))
; __device__ __forceinline__ float fast_exp2(float x) { return __builtin_amdgcn_exp2f(x); }
; __device__ __forceinline__ float fast_log2(float x) { return __builtin_amdgcn_logf(x); }
; __device__ __forceinline__ float min2f(float a, float b) { float r; asm("v_min_f32_e32 %0, %1, %2" : "=v"(r) : "v"(a), "v"(b)); return r; }
; __device__ __forceinline__ float max2f(float a, float b) { float r; asm("v_max_f32_e32 %0, %1, %2" : "=v"(r) : "v"(a), "v"(b)); return r; }
; #define MFMA32(a, b, c) __builtin_amdgcn_mfma_f32_32x32x16_bf16((a), (b), (c), 0, 0, 0)
; __device__ __forceinline__ void sb_tile_math(f32x16& s0, f32x16& s1, float& carry, int kb, int tw, int t_row, int hi) {
;             if (kb + 64 > tw) { const int rel = t_row - kb - 8 * hi;
; #pragma unroll
;                 for (int r = 0; r < 16; ++r) { s0[r] = ((16 * (r >> 3) + (r & 7)) < rel) ? s0[r] : -1e30f; s1[r] = ((32 + 16 * (r >> 3) + (r & 7)) < rel) ? s1[r] : -1e30f; } }
;             f32x16 lk0, lk1;
;             asm volatile("s_nop 15\n\ts_nop 7" : "+v"(s0), "+v"(s1));
;             { float zf = 0.f; asm volatile("" : "+v"(zf));
; #pragma unroll
;               for (int r = 0; r < 16; ++r) {
;                 { const float x = s0[r], lg = fast_log2(1.0f + fast_exp2(-__builtin_fabsf(x))); lk0[r] = -(max2f(x, zf) + lg); s0[r] = min2f(x, zf) - lg; }
; __device__ __forceinline__ void sb_unit(LAS unsigned char* lds, const bf16_t* __restrict__ u, bf16_t* __restrict__ yz, int b, int h, int qb) {
;     ...
;                 for (int d0 = 0; d0 < 4; ++d0) { kf_[2 * d0] = *(LAS const bf16x8*)(lds + so + kfa[d0]); kf_[2 * d0 + 1] = *(LAS const bf16x8*)(lds + so + kfa[d0] + 4096); }
;                 f32x16 s0 = MFMA32(kf_[0], qf[0], zero16), s1 = MFMA32(kf_[1], qf[0], zero16);
; #pragma unroll
;                 for (int d0 = 1; d0 < 4; ++d0) { s0 = MFMA32(kf_[2 * d0], qf[d0], s0); s1 = MFMA32(kf_[2 * d0 + 1], qf[d0], s1); }
;                 sb_tile_math(s0, s1, carry, kb, tw, t_row, hi);
.LBB0_320:
	v_readlane_b32 s10, v232, 61
	s_nop 3
	s_cmp_lg_u32 s10, 1
	s_cbranch_scc1 .Lsb_no_stage2
	s_waitcnt vmcnt(0)
	s_barrier
.Lsb_no_stage2:
	s_add_i32 s10, s10, 1
	v_writelane_b32 v232, s10, 61
	v_add_u32_e32 v38, s24, v174
	ds_read_b128 v[34:37], v38
	v_add_u32_e32 v92, s24, v173
	ds_read_b128 v[88:91], v92
	s_cmp_le_u32 s27, s15
	s_waitcnt lgkmcnt(1)
	v_mfma_f32_32x32x16_bf16 v[50:65], v[34:37], v[66:69], 0
	ds_read_b128 v[34:37], v38 offset:4096
	s_waitcnt lgkmcnt(1)
	v_mfma_f32_32x32x16_bf16 v[50:65], v[88:91], v[70:73], v[50:65]
	ds_read_b128 v[88:91], v92 offset:4096
	v_add_u32_e32 v92, s24, v172
	s_waitcnt lgkmcnt(1)
	v_mfma_f32_32x32x16_bf16 v[34:49], v[34:37], v[66:69], 0
	s_waitcnt lgkmcnt(0)
	v_mfma_f32_32x32x16_bf16 v[34:49], v[88:91], v[70:73], v[34:49]
	ds_read_b128 v[88:91], v92
	s_waitcnt lgkmcnt(0)
	v_mfma_f32_32x32x16_bf16 v[50:65], v[88:91], v[74:77], v[50:65]
	ds_read_b128 v[88:91], v92 offset:4096
	v_add_u32_e32 v92, s24, v171
	s_waitcnt lgkmcnt(0)
	v_mfma_f32_32x32x16_bf16 v[34:49], v[88:91], v[74:77], v[34:49]
	ds_read_b128 v[88:91], v92
	s_waitcnt lgkmcnt(0)
	v_mfma_f32_32x32x16_bf16 v[50:65], v[88:91], v[78:81], v[50:65]
	ds_read_b128 v[88:91], v92 offset:4096
	s_waitcnt lgkmcnt(0)
	v_mfma_f32_32x32x16_bf16 v[34:49], v[88:91], v[78:81], v[34:49]
	s_cbranch_scc1 .LBB0_322
	v_cmp_lt_i32_e32 vcc, 0, v0
	s_nop 6
	v_cndmask_b32_e32 v50, v167, v50, vcc
	v_cmp_lt_i32_e32 vcc, 32, v0
	s_nop 1
	v_cndmask_b32_e32 v34, v167, v34, vcc
	v_cmp_lt_i32_e32 vcc, 1, v0
	s_nop 1
	v_cndmask_b32_e32 v51, v167, v51, vcc
	v_cmp_lt_i32_e32 vcc, 33, v0
	s_nop 1
	v_cndmask_b32_e32 v35, v167, v35, vcc
	v_cmp_lt_i32_e32 vcc, 2, v0
	s_nop 1
	v_cndmask_b32_e32 v52, v167, v52, vcc
	v_cmp_lt_i32_e32 vcc, 34, v0
	s_nop 1
	v_cndmask_b32_e32 v36, v167, v36, vcc
	v_cmp_lt_i32_e32 vcc, 3, v0
	s_nop 1
	v_cndmask_b32_e32 v53, v167, v53, vcc
	v_cmp_lt_i32_e32 vcc, 35, v0
	s_nop 1
	v_cndmask_b32_e32 v37, v167, v37, vcc
	v_cmp_lt_i32_e32 vcc, 4, v0
	s_nop 1
	v_cndmask_b32_e32 v54, v167, v54, vcc
	v_cmp_lt_i32_e32 vcc, 36, v0
	s_nop 1
	v_cndmask_b32_e32 v38, v167, v38, vcc
	v_cmp_lt_i32_e32 vcc, 5, v0
	s_nop 1
	v_cndmask_b32_e32 v55, v167, v55, vcc
	v_cmp_lt_i32_e32 vcc, 37, v0
	s_nop 1
	v_cndmask_b32_e32 v39, v167, v39, vcc
	v_cmp_lt_i32_e32 vcc, 6, v0
	s_nop 1
	v_cndmask_b32_e32 v56, v167, v56, vcc
	v_cmp_lt_i32_e32 vcc, 38, v0
	s_nop 1
	v_cndmask_b32_e32 v40, v167, v40, vcc
	v_cmp_lt_i32_e32 vcc, 7, v0
	s_nop 1
	v_cndmask_b32_e32 v57, v167, v57, vcc
	v_cmp_lt_i32_e32 vcc, 39, v0
	s_nop 1
	v_cndmask_b32_e32 v41, v167, v41, vcc
	v_cmp_lt_i32_e32 vcc, 16, v0
	s_nop 1
	v_cndmask_b32_e32 v58, v167, v58, vcc
	v_cmp_lt_i32_e32 vcc, 48, v0
	s_nop 1
	v_cndmask_b32_e32 v42, v167, v42, vcc
	v_cmp_lt_i32_e32 vcc, 17, v0
	s_nop 1
	v_cndmask_b32_e32 v59, v167, v59, vcc
	v_cmp_lt_i32_e32 vcc, 49, v0
	s_nop 1
	v_cndmask_b32_e32 v43, v167, v43, vcc
	v_cmp_lt_i32_e32 vcc, 18, v0
	s_nop 1
	v_cndmask_b32_e32 v60, v167, v60, vcc
	v_cmp_lt_i32_e32 vcc, 50, v0
	s_nop 1
	v_cndmask_b32_e32 v44, v167, v44, vcc
	v_cmp_lt_i32_e32 vcc, 19, v0
	s_nop 1
	v_cndmask_b32_e32 v61, v167, v61, vcc
	v_cmp_lt_i32_e32 vcc, 51, v0
	s_nop 1
	v_cndmask_b32_e32 v45, v167, v45, vcc
	v_cmp_lt_i32_e32 vcc, 20, v0
	s_nop 1
	v_cndmask_b32_e32 v62, v167, v62, vcc
	v_cmp_lt_i32_e32 vcc, 52, v0
	s_nop 1
	v_cndmask_b32_e32 v46, v167, v46, vcc
	v_cmp_lt_i32_e32 vcc, 21, v0
	s_nop 1
	v_cndmask_b32_e32 v63, v167, v63, vcc
	v_cmp_lt_i32_e32 vcc, 53, v0
	s_nop 1
	v_cndmask_b32_e32 v47, v167, v47, vcc
	v_cmp_lt_i32_e32 vcc, 22, v0
	s_nop 1
	v_cndmask_b32_e32 v64, v167, v64, vcc
	v_cmp_lt_i32_e32 vcc, 54, v0
	s_nop 1
	v_cndmask_b32_e32 v48, v167, v48, vcc
	v_cmp_lt_i32_e32 vcc, 23, v0
	s_nop 1
	v_cndmask_b32_e32 v65, v167, v65, vcc
	v_cmp_lt_i32_e32 vcc, 55, v0
	s_nop 1
	v_cndmask_b32_e32 v49, v167, v49, vcc
.LBB0_322:
	v_add_u32_e32 v204, s24, v170
	v_add_u32_e32 v205, s24, v169
	v_xor_b32_e32 v206, 32, v162
	v_lshlrev_b32_e32 v206, 2, v206
	s_nop 15
	v_exp_f32_e64 v120, -|v50|
	v_exp_f32_e64 v121, -|v51|
	v_exp_f32_e64 v122, -|v52|
	v_exp_f32_e64 v123, -|v53|
	v_exp_f32_e64 v124, -|v54|
	v_exp_f32_e64 v125, -|v55|
	v_exp_f32_e64 v126, -|v56|
	v_exp_f32_e64 v127, -|v57|
	v_exp_f32_e64 v128, -|v58|
	v_exp_f32_e64 v129, -|v59|
	v_exp_f32_e64 v130, -|v60|
	v_exp_f32_e64 v131, -|v61|
	v_exp_f32_e64 v132, -|v62|
	v_exp_f32_e64 v133, -|v63|
	v_exp_f32_e64 v134, -|v64|
	v_exp_f32_e64 v135, -|v65|
	v_exp_f32_e64 v136, -|v34|
	v_exp_f32_e64 v137, -|v35|
	v_exp_f32_e64 v138, -|v36|
	v_exp_f32_e64 v139, -|v37|
	v_exp_f32_e64 v142, -|v38|
	v_exp_f32_e64 v143, -|v39|
	v_exp_f32_e64 v144, -|v40|
	v_exp_f32_e64 v145, -|v41|
	v_exp_f32_e64 v146, -|v42|
	v_exp_f32_e64 v147, -|v43|
	v_exp_f32_e64 v148, -|v44|
	v_exp_f32_e64 v149, -|v45|
	v_exp_f32_e64 v150, -|v46|
	v_exp_f32_e64 v151, -|v47|
	v_exp_f32_e64 v152, -|v48|
	v_exp_f32_e64 v153, -|v49|
	v_max_f32_e32 v154, 0, v50
	v_max_f32_e32 v155, 0, v51
	v_max_f32_e32 v156, 0, v52
	v_max_f32_e32 v157, 0, v53
	v_max_f32_e32 v158, 0, v54
	v_max_f32_e32 v159, 0, v55
	v_max_f32_e32 v178, 0, v56
	v_max_f32_e32 v179, 0, v57
	v_max_f32_e32 v180, 0, v58
	v_max_f32_e32 v181, 0, v59
	v_max_f32_e32 v182, 0, v60
	v_max_f32_e32 v183, 0, v61
	v_max_f32_e32 v184, 0, v62
	v_max_f32_e32 v185, 0, v63
	v_max_f32_e32 v186, 0, v64
	v_max_f32_e32 v187, 0, v65
	v_max_f32_e32 v188, 0, v34
	v_max_f32_e32 v189, 0, v35
	v_max_f32_e32 v190, 0, v36
	v_max_f32_e32 v191, 0, v37
	v_max_f32_e32 v192, 0, v38
	v_max_f32_e32 v193, 0, v39
	v_max_f32_e32 v194, 0, v40
	v_max_f32_e32 v195, 0, v41
	v_max_f32_e32 v196, 0, v42
	v_max_f32_e32 v197, 0, v43
	v_max_f32_e32 v198, 0, v44
	v_max_f32_e32 v199, 0, v45
; __device__ __forceinline__ float fast_exp2(float x) { return __builtin_amdgcn_exp2f(x); }
; __device__ __forceinline__ float fast_log2(float x) { return __builtin_amdgcn_logf(x); }
; __device__ __forceinline__ float min2f(float a, float b) { float r; asm("v_min_f32_e32 %0, %1, %2" : "=v"(r) : "v"(a), "v"(b)); return r; }
; __device__ __forceinline__ float max2f(float a, float b) { float r; asm("v_max_f32_e32 %0, %1, %2" : "=v"(r) : "v"(a), "v"(b)); return r; }
; __device__ __forceinline__ s16x4 vtr(LAS unsigned char* p) { return __builtin_bit_cast(s16x4, __builtin_amdgcn_ds_read_tr16_b64_v4i16((LAS v4i16_t*)p)); }
; __device__ __forceinline__ void sb_tile_math(f32x16& s0, f32x16& s1, float& carry, int kb, int tw, int t_row, int hi) {
;     ...
;               for (int r = 0; r < 16; ++r) {
;                 { const float x = s0[r], lg = fast_log2(1.0f + fast_exp2(-__builtin_fabsf(x))); lk0[r] = -(max2f(x, zf) + lg); s0[r] = min2f(x, zf) - lg; }
;                 { const float x = s1[r], lg = fast_log2(1.0f + fast_exp2(-__builtin_fabsf(x))); lk1[r] = -(max2f(x, zf) + lg); s1[r] = min2f(x, zf) - lg; }
;               } }
;             float R00 = 0.f, R01 = 0.f, R10 = 0.f, R11 = 0.f;
; #pragma unroll
;             for (int j = 0; j < 8; ++j) { R00 += lk0[j]; R01 += lk0[8 + j]; R10 += lk1[j]; R11 += lk1[8 + j]; }
;             const float P00 = __shfl_xor(R00, 32), P01 = __shfl_xor(R01, 32), P10 = __shfl_xor(R10, 32), P11 = __shfl_xor(R11, 32);
; __device__ __forceinline__ void sb_unit(LAS unsigned char* lds, const bf16_t* __restrict__ u, bf16_t* __restrict__ yz, int b, int h, int qb) {
;     ...
;                     const s16x4 a0 = vtr(lds + so + vra[0][0] + ks * 2048), a1 = vtr(lds + so + vra[0][1] + ks * 2048);
;                     const s16x4 c0 = vtr(lds + so + vra[1][0] + ks * 2048), c1 = vtr(lds + so + vra[1][1] + ks * 2048);
;                     const bf16x8 v0 = (bf16x8){a0[0], a0[1], a0[2], a0[3], a1[0], a1[1], a1[2], a1[3]};
;                     const bf16x8 v1 = (bf16x8){c0[0], c0[1], c0[2], c0[3], c1[0], c1[1], c1[2], c1[3]};
	v_max_f32_e32 v200, 0, v46
	v_max_f32_e32 v201, 0, v47
	v_max_f32_e32 v202, 0, v48
	v_max_f32_e32 v203, 0, v49
	v_pk_add_f32 v[120:121], v[120:121], 1.0 op_sel_hi:[1,0]
	v_pk_add_f32 v[122:123], v[122:123], 1.0 op_sel_hi:[1,0]
	v_pk_add_f32 v[124:125], v[124:125], 1.0 op_sel_hi:[1,0]
	v_pk_add_f32 v[126:127], v[126:127], 1.0 op_sel_hi:[1,0]
	v_pk_add_f32 v[128:129], v[128:129], 1.0 op_sel_hi:[1,0]
	v_pk_add_f32 v[130:131], v[130:131], 1.0 op_sel_hi:[1,0]
	v_pk_add_f32 v[132:133], v[132:133], 1.0 op_sel_hi:[1,0]
	v_pk_add_f32 v[134:135], v[134:135], 1.0 op_sel_hi:[1,0]
	v_pk_add_f32 v[136:137], v[136:137], 1.0 op_sel_hi:[1,0]
	v_pk_add_f32 v[138:139], v[138:139], 1.0 op_sel_hi:[1,0]
	v_pk_add_f32 v[142:143], v[142:143], 1.0 op_sel_hi:[1,0]
	v_pk_add_f32 v[144:145], v[144:145], 1.0 op_sel_hi:[1,0]
	v_pk_add_f32 v[146:147], v[146:147], 1.0 op_sel_hi:[1,0]
	v_pk_add_f32 v[148:149], v[148:149], 1.0 op_sel_hi:[1,0]
	v_pk_add_f32 v[150:151], v[150:151], 1.0 op_sel_hi:[1,0]
	v_pk_add_f32 v[152:153], v[152:153], 1.0 op_sel_hi:[1,0]
	v_min_f32_e32 v50, 0, v50
	v_min_f32_e32 v51, 0, v51
	v_min_f32_e32 v52, 0, v52
	v_min_f32_e32 v53, 0, v53
	v_min_f32_e32 v54, 0, v54
	v_min_f32_e32 v55, 0, v55
	v_min_f32_e32 v56, 0, v56
	v_min_f32_e32 v57, 0, v57
	v_min_f32_e32 v58, 0, v58
	v_min_f32_e32 v59, 0, v59
	v_min_f32_e32 v60, 0, v60
	v_min_f32_e32 v61, 0, v61
	v_min_f32_e32 v62, 0, v62
	v_min_f32_e32 v63, 0, v63
	v_min_f32_e32 v64, 0, v64
	v_min_f32_e32 v65, 0, v65
	v_min_f32_e32 v34, 0, v34
	v_min_f32_e32 v35, 0, v35
	v_min_f32_e32 v36, 0, v36
	v_min_f32_e32 v37, 0, v37
	v_min_f32_e32 v38, 0, v38
	v_min_f32_e32 v39, 0, v39
	v_min_f32_e32 v40, 0, v40
	v_min_f32_e32 v41, 0, v41
	v_min_f32_e32 v42, 0, v42
	v_min_f32_e32 v43, 0, v43
	v_min_f32_e32 v44, 0, v44
	v_min_f32_e32 v45, 0, v45
	v_min_f32_e32 v46, 0, v46
	v_min_f32_e32 v47, 0, v47
	v_min_f32_e32 v48, 0, v48
	v_min_f32_e32 v49, 0, v49
	v_log_f32_e32 v120, v120
	v_log_f32_e32 v121, v121
	v_log_f32_e32 v122, v122
	v_log_f32_e32 v123, v123
	v_log_f32_e32 v124, v124
	v_log_f32_e32 v125, v125
	v_log_f32_e32 v126, v126
	v_log_f32_e32 v127, v127
	v_log_f32_e32 v128, v128
	v_log_f32_e32 v129, v129
	v_log_f32_e32 v130, v130
	v_log_f32_e32 v131, v131
	v_log_f32_e32 v132, v132
	v_log_f32_e32 v133, v133
	v_log_f32_e32 v134, v134
	v_log_f32_e32 v135, v135
	v_log_f32_e32 v136, v136
	v_log_f32_e32 v137, v137
	v_log_f32_e32 v138, v138
	v_log_f32_e32 v139, v139
	v_log_f32_e32 v142, v142
	v_log_f32_e32 v143, v143
	v_log_f32_e32 v144, v144
	v_log_f32_e32 v145, v145
	v_log_f32_e32 v146, v146
	v_log_f32_e32 v147, v147
	v_log_f32_e32 v148, v148
	v_log_f32_e32 v149, v149
	v_log_f32_e32 v150, v150
	v_log_f32_e32 v151, v151
	v_log_f32_e32 v152, v152
	v_log_f32_e32 v153, v153
	ds_read_b64_tr_b16 v[88:89], v204 offset:8192
	ds_read_b64_tr_b16 v[90:91], v205 offset:8704
	ds_read_b64_tr_b16 v[92:93], v205 offset:8192
	ds_read_b64_tr_b16 v[94:95], v204 offset:8704
	ds_read_b64_tr_b16 v[96:97], v204 offset:10240
	ds_read_b64_tr_b16 v[98:99], v205 offset:10752
	ds_read_b64_tr_b16 v[100:101], v205 offset:10240
	ds_read_b64_tr_b16 v[102:103], v204 offset:10752
	ds_read_b64_tr_b16 v[104:105], v204 offset:12288
	ds_read_b64_tr_b16 v[106:107], v205 offset:12800
	ds_read_b64_tr_b16 v[108:109], v205 offset:12288
	ds_read_b64_tr_b16 v[110:111], v204 offset:12800
	ds_read_b64_tr_b16 v[112:113], v204 offset:14336
	ds_read_b64_tr_b16 v[114:115], v205 offset:14848
	ds_read_b64_tr_b16 v[116:117], v205 offset:14336
	ds_read_b64_tr_b16 v[118:119], v204 offset:14848
	v_pk_add_f32 v[154:155], v[154:155], v[120:121]
	v_pk_add_f32 v[156:157], v[156:157], v[122:123]
	v_pk_add_f32 v[158:159], v[158:159], v[124:125]
	v_pk_add_f32 v[178:179], v[178:179], v[126:127]
	v_pk_add_f32 v[180:181], v[180:181], v[128:129]
	v_pk_add_f32 v[182:183], v[182:183], v[130:131]
	v_pk_add_f32 v[184:185], v[184:185], v[132:133]
	v_pk_add_f32 v[186:187], v[186:187], v[134:135]
	v_pk_add_f32 v[188:189], v[188:189], v[136:137]
	v_pk_add_f32 v[190:191], v[190:191], v[138:139]
	v_pk_add_f32 v[192:193], v[192:193], v[142:143]
	v_pk_add_f32 v[194:195], v[194:195], v[144:145]
	v_pk_add_f32 v[196:197], v[196:197], v[146:147]
	v_pk_add_f32 v[198:199], v[198:199], v[148:149]
	v_pk_add_f32 v[200:201], v[200:201], v[150:151]
	v_pk_add_f32 v[202:203], v[202:203], v[152:153]
	v_pk_add_f32 v[50:51], v[50:51], v[120:121] neg_lo:[0,1] neg_hi:[0,1]
	v_pk_add_f32 v[52:53], v[52:53], v[122:123] neg_lo:[0,1] neg_hi:[0,1]
	v_pk_add_f32 v[54:55], v[54:55], v[124:125] neg_lo:[0,1] neg_hi:[0,1]
	v_pk_add_f32 v[56:57], v[56:57], v[126:127] neg_lo:[0,1] neg_hi:[0,1]
	v_pk_add_f32 v[58:59], v[58:59], v[128:129] neg_lo:[0,1] neg_hi:[0,1]
	v_pk_add_f32 v[60:61], v[60:61], v[130:131] neg_lo:[0,1] neg_hi:[0,1]
	v_pk_add_f32 v[62:63], v[62:63], v[132:133] neg_lo:[0,1] neg_hi:[0,1]
	v_pk_add_f32 v[64:65], v[64:65], v[134:135] neg_lo:[0,1] neg_hi:[0,1]
	v_pk_add_f32 v[34:35], v[34:35], v[136:137] neg_lo:[0,1] neg_hi:[0,1]
	v_pk_add_f32 v[36:37], v[36:37], v[138:139] neg_lo:[0,1] neg_hi:[0,1]
	v_pk_add_f32 v[38:39], v[38:39], v[142:143] neg_lo:[0,1] neg_hi:[0,1]
	v_pk_add_f32 v[40:41], v[40:41], v[144:145] neg_lo:[0,1] neg_hi:[0,1]
	v_pk_add_f32 v[42:43], v[42:43], v[146:147] neg_lo:[0,1] neg_hi:[0,1]
	v_pk_add_f32 v[44:45], v[44:45], v[148:149] neg_lo:[0,1] neg_hi:[0,1]
	v_pk_add_f32 v[46:47], v[46:47], v[150:151] neg_lo:[0,1] neg_hi:[0,1]
	v_pk_add_f32 v[48:49], v[48:49], v[152:153] neg_lo:[0,1] neg_hi:[0,1]
	v_pk_add_f32 v[120:121], v[154:155], v[156:157]
	v_pk_add_f32 v[128:129], v[158:159], v[178:179]
	v_pk_add_f32 v[122:123], v[180:181], v[182:183]
	v_pk_add_f32 v[130:131], v[184:185], v[186:187]
	v_pk_add_f32 v[124:125], v[188:189], v[190:191]
	v_pk_add_f32 v[132:133], v[192:193], v[194:195]
	v_pk_add_f32 v[126:127], v[196:197], v[198:199]
	v_pk_add_f32 v[134:135], v[200:201], v[202:203]
	v_pk_add_f32 v[120:121], v[120:121], v[128:129]
	v_pk_add_f32 v[122:123], v[122:123], v[130:131]
	v_pk_add_f32 v[124:125], v[124:125], v[132:133]
	v_pk_add_f32 v[126:127], v[126:127], v[134:135]
	v_add_f32_e32 v136, v120, v121
	v_add_f32_e32 v137, v122, v123
	v_add_f32_e32 v138, v124, v125
	v_add_f32_e32 v139, v126, v127
	ds_bpermute_b32 v142, v206, v136
	ds_bpermute_b32 v143, v206, v137
	ds_bpermute_b32 v144, v206, v138
	ds_bpermute_b32 v145, v206, v139
	s_waitcnt lgkmcnt(0)
; __device__ __forceinline__ float fast_exp2(float x) { return __builtin_amdgcn_exp2f(x); }
; __device__ __forceinline__ void sb_tile_math(f32x16& s0, f32x16& s1, float& carry, int kb, int tw, int t_row, int hi) {
;     ...
;             const float T11 = R11 + P11, T10 = R10 + P10, T01 = R01 + P01, T00 = R00 + P00;
;             const float off11 = carry + (hi == 0 ? P11 : 0.f);
;             const float off10 = carry + T11 + (hi == 0 ? P10 : 0.f);
;             const float off01 = carry + T11 + T10 + (hi == 0 ? P01 : 0.f);
;             const float off00 = carry + T11 + T10 + T01 + (hi == 0 ? P00 : 0.f);
;             carry += (T11 + T10) + (T01 + T00);
;             { float a = off00;
; #pragma unroll
;               for (int j = 7; j >= 0; --j) { const float bt = a; a += lk0[j]; s0[j] = fast_exp2(s0[j] + bt); } }
;             { float a = off01;
; #pragma unroll
;               for (int j = 7; j >= 0; --j) { const float bt = a; a += lk0[8 + j]; s0[8 + j] = fast_exp2(s0[8 + j] + bt); } }
;             { float a = off10;
; #pragma unroll
;               for (int j = 7; j >= 0; --j) { const float bt = a; a += lk1[j]; s1[j] = fast_exp2(s1[j] + bt); } }
;             { float a = off11;
; #pragma unroll
;               for (int j = 7; j >= 0; --j) { const float bt = a; a += lk1[8 + j]; s1[8 + j] = fast_exp2(s1[8 + j] + bt); } }
; __device__ __forceinline__ void sb_unit(LAS unsigned char* lds, const bf16_t* __restrict__ u, bf16_t* __restrict__ yz, int b, int h, int qb) {
;     ...
;                 bf16x8 pf[4];
;                 { u32x4 w;
;                   w.x = cvt_pk_bf16(s0[0], s0[1]); w.y = cvt_pk_bf16(s0[2], s0[3]); w.z = cvt_pk_bf16(s0[4], s0[5]); w.w = cvt_pk_bf16(s0[6], s0[7]); pf[0] = __builtin_bit_cast(bf16x8, w);
;                   w.x = cvt_pk_bf16(s0[8], s0[9]); w.y = cvt_pk_bf16(s0[10], s0[11]); w.z = cvt_pk_bf16(s0[12], s0[13]); w.w = cvt_pk_bf16(s0[14], s0[15]); pf[1] = __builtin_bit_cast(bf16x8, w);
;                   w.x = cvt_pk_bf16(s1[0], s1[1]); w.y = cvt_pk_bf16(s1[2], s1[3]); w.z = cvt_pk_bf16(s1[4], s1[5]); w.w = cvt_pk_bf16(s1[6], s1[7]); pf[2] = __builtin_bit_cast(bf16x8, w);
;                   w.x = cvt_pk_bf16(s1[8], s1[9]); w.y = cvt_pk_bf16(s1[10], s1[11]); w.z = cvt_pk_bf16(s1[12], s1[13]); w.w = cvt_pk_bf16(s1[14], s1[15]); pf[3] = __builtin_bit_cast(bf16x8, w); }
; #pragma unroll
;                 for (int ks = 0; ks < 4; ++ks) {
	v_cndmask_b32_e64 v146, 0, v142, s[4:5]
	v_cndmask_b32_e64 v147, 0, v143, s[4:5]
	v_cndmask_b32_e64 v148, 0, v144, s[4:5]
	v_cndmask_b32_e64 v149, 0, v145, s[4:5]
	v_add_f32_e32 v142, v136, v142
	v_add_f32_e32 v143, v137, v143
	v_add_f32_e32 v144, v138, v144
	v_add_f32_e32 v145, v139, v145
	v_sub_f32_e32 v136, v176, v145
	v_add_f32_e32 v139, v145, v144
	v_add_f32_e32 v207, v143, v142
	v_sub_f32_e32 v153, v176, v149
	v_sub_f32_e32 v137, v136, v144
	v_add_f32_e32 v139, v139, v207
	v_sub_f32_e32 v152, v136, v148
	v_sub_f32_e32 v138, v137, v143
	v_sub_f32_e32 v151, v137, v147
	v_sub_f32_e32 v176, v176, v139
	v_sub_f32_e32 v150, v138, v146
	v_add_f32_e32 v57, v57, v150
	v_add_f32_e32 v65, v65, v151
	v_add_f32_e32 v41, v41, v152
	v_add_f32_e32 v49, v49, v153
	v_sub_f32_e32 v150, v150, v179
	v_sub_f32_e32 v151, v151, v187
	v_sub_f32_e32 v152, v152, v195
	v_sub_f32_e32 v153, v153, v203
	v_exp_f32_e32 v57, v57
	v_exp_f32_e32 v65, v65
	v_exp_f32_e32 v41, v41
	v_exp_f32_e32 v49, v49
	v_add_f32_e32 v56, v56, v150
	v_add_f32_e32 v64, v64, v151
	v_add_f32_e32 v40, v40, v152
	v_add_f32_e32 v48, v48, v153
	v_sub_f32_e32 v150, v150, v178
	v_sub_f32_e32 v151, v151, v186
	v_sub_f32_e32 v152, v152, v194
	v_sub_f32_e32 v153, v153, v202
	v_exp_f32_e32 v56, v56
	v_exp_f32_e32 v64, v64
	v_exp_f32_e32 v40, v40
	v_exp_f32_e32 v48, v48
	v_add_f32_e32 v55, v55, v150
	v_add_f32_e32 v63, v63, v151
	v_add_f32_e32 v39, v39, v152
	v_add_f32_e32 v47, v47, v153
	v_sub_f32_e32 v150, v150, v159
	v_sub_f32_e32 v151, v151, v185
	v_sub_f32_e32 v152, v152, v193
	v_sub_f32_e32 v153, v153, v201
	v_exp_f32_e32 v55, v55
	v_exp_f32_e32 v63, v63
	v_exp_f32_e32 v39, v39
	v_exp_f32_e32 v47, v47
	v_add_f32_e32 v54, v54, v150
	v_add_f32_e32 v62, v62, v151
	v_add_f32_e32 v38, v38, v152
	v_add_f32_e32 v46, v46, v153
	v_sub_f32_e32 v150, v150, v158
	v_sub_f32_e32 v151, v151, v184
	v_sub_f32_e32 v152, v152, v192
	v_sub_f32_e32 v153, v153, v200
	v_exp_f32_e32 v54, v54
	v_exp_f32_e32 v62, v62
	v_exp_f32_e32 v38, v38
	v_exp_f32_e32 v46, v46
	v_add_f32_e32 v53, v53, v150
	v_add_f32_e32 v61, v61, v151
	v_add_f32_e32 v37, v37, v152
	v_add_f32_e32 v45, v45, v153
	v_sub_f32_e32 v150, v150, v157
	v_sub_f32_e32 v151, v151, v183
	v_sub_f32_e32 v152, v152, v191
	v_sub_f32_e32 v153, v153, v199
	v_exp_f32_e32 v53, v53
	v_exp_f32_e32 v61, v61
	v_exp_f32_e32 v37, v37
	v_exp_f32_e32 v45, v45
	v_add_f32_e32 v52, v52, v150
	v_add_f32_e32 v60, v60, v151
	v_add_f32_e32 v36, v36, v152
	v_add_f32_e32 v44, v44, v153
	v_sub_f32_e32 v150, v150, v156
	v_sub_f32_e32 v151, v151, v182
	v_sub_f32_e32 v152, v152, v190
	v_sub_f32_e32 v153, v153, v198
	v_exp_f32_e32 v52, v52
	v_exp_f32_e32 v60, v60
	v_exp_f32_e32 v36, v36
	v_exp_f32_e32 v44, v44
	v_add_f32_e32 v51, v51, v150
	v_add_f32_e32 v59, v59, v151
	v_add_f32_e32 v35, v35, v152
	v_add_f32_e32 v43, v43, v153
	v_sub_f32_e32 v150, v150, v155
	v_sub_f32_e32 v151, v151, v181
	v_sub_f32_e32 v152, v152, v189
	v_sub_f32_e32 v153, v153, v197
	v_exp_f32_e32 v51, v51
	v_exp_f32_e32 v59, v59
	v_exp_f32_e32 v35, v35
	v_exp_f32_e32 v43, v43
	v_add_f32_e32 v50, v50, v150
	v_add_f32_e32 v58, v58, v151
	v_add_f32_e32 v34, v34, v152
	v_add_f32_e32 v42, v42, v153
	v_exp_f32_e32 v50, v50
	v_exp_f32_e32 v58, v58
	v_exp_f32_e32 v34, v34
	v_exp_f32_e32 v42, v42
	s_nop 0
	v_cvt_pk_bf16_f32 v120, v50, v51
	v_cvt_pk_bf16_f32 v121, v52, v53
	v_cvt_pk_bf16_f32 v122, v54, v55
	v_cvt_pk_bf16_f32 v123, v56, v57
	v_cvt_pk_bf16_f32 v124, v58, v59
	v_cvt_pk_bf16_f32 v125, v60, v61
	v_cvt_pk_bf16_f32 v126, v62, v63
	v_cvt_pk_bf16_f32 v127, v64, v65
	v_cvt_pk_bf16_f32 v128, v34, v35
	v_cvt_pk_bf16_f32 v129, v36, v37
	v_cvt_pk_bf16_f32 v130, v38, v39
	v_cvt_pk_bf16_f32 v131, v40, v41
	v_cvt_pk_bf16_f32 v132, v42, v43
	v_cvt_pk_bf16_f32 v133, v44, v45
	v_cvt_pk_bf16_f32 v134, v46, v47
	v_cvt_pk_bf16_f32 v135, v48, v49
	s_waitcnt lgkmcnt(0)
	s_nop 0
	v_mfma_f32_32x32x16_bf16 v[18:33], v[88:91], v[120:123], v[18:33]
	v_mfma_f32_32x32x16_bf16 v[2:17], v[92:95], v[120:123], v[2:17]
	v_mfma_f32_32x32x16_bf16 v[18:33], v[96:99], v[124:127], v[18:33]
	v_mfma_f32_32x32x16_bf16 v[2:17], v[100:103], v[124:127], v[2:17]
	v_mfma_f32_32x32x16_bf16 v[18:33], v[104:107], v[128:131], v[18:33]
	v_mfma_f32_32x32x16_bf16 v[2:17], v[108:111], v[128:131], v[2:17]
	v_mfma_f32_32x32x16_bf16 v[18:33], v[112:115], v[132:135], v[18:33]
	v_mfma_f32_32x32x16_bf16 v[2:17], v[116:119], v[132:135], v[2:17]
	v_cmp_gt_f32_e32 vcc, s85, v176
	s_cmp_eq_u64 vcc, exec
	s_cselect_b64 s[10:11], -1, 0
	s_and_b64 s[12:13], s[10:11], exec
	s_cselect_b32 s28, 23, 0
	s_or_b64 s[8:9], s[10:11], s[8:9]
	s_mov_b64 s[10:11], -1
	s_cmp_gt_i32 s28, 24
	s_mov_b64 s[12:13], -1
	s_cbranch_scc1 .LBB0_318

; #define WAITV_BAR(N) asm volatile("s_waitcnt vmcnt(" #N ") lgkmcnt(0)\n\ts_barrier" ::: "memory")
; __device__ __forceinline__ void sb_unit(LAS unsigned char* lds, const bf16_t* __restrict__ u, bf16_t* __restrict__ yz, int b, int h, int qb) {
;     ...
;         WAITV_BAR(0);
;         if (!done) {
;             for (int i = 0; i < 8; ++i) { const int kt = kt_hi - i; if (kt < 0) { done = true; break; }
.LBB0_325:
	v_readlane_b32 s10, v232, 61
	s_nop 3
	s_cmp_gt_u32 s10, 1
	s_cbranch_scc1 .Lsb_stage2_done
	s_waitcnt vmcnt(0)
	s_barrier

; __device__ __forceinline__ void sb_unit(LAS unsigned char* lds, const bf16_t* __restrict__ u, bf16_t* __restrict__ yz, int b, int h, int qb) {
;     ...
;         for (int i = 0; i < 8; ++i) { const int kk = kt_hi - i;
;             if (kk >= 0) { const unsigned d_ = (unsigned)__builtin_amdgcn_readfirstlane(lds0 + i * 16384 + wid * 1024);
;                 glds16(kgb + (size_t)kk * (64 * NIN * 2), koff, d_); glds16(vgb + (size_t)kk * (64 * NIN * 2), voff, d_ + 8192); } }
.LBB0_328:
	s_add_i32 s10, s96, -2
	s_mov_b32 s11, s97
	s_lshl_b64 s[10:11], s[10:11], 14
	s_add_u32 s12, s20, s10
	s_addc_u32 s13, s21, s11
	s_add_u32 s10, s17, s10
	s_addc_u32 s11, s18, s11
	s_add_i32 s24, s22, 0x8000
	s_mov_b32 s25, m0
	s_mov_b32 m0, s24
	s_nop 0
	global_load_lds_dwordx4 v168, s[10:11]
	s_mov_b32 m0, s25
	s_add_i32 s10, s22, 0xa000
	s_mov_b32 s11, m0
	s_mov_b32 m0, s10
	s_nop 0
	global_load_lds_dwordx4 v87, s[12:13]
	s_mov_b32 m0, s11
	s_cmp_lt_u32 s96, 3
	s_cbranch_scc1 .LBB0_307
.LBB0_329:
	s_add_i32 s10, s96, -3
	s_mov_b32 s11, s97
	s_lshl_b64 s[10:11], s[10:11], 14
	s_add_u32 s12, s20, s10
	s_addc_u32 s13, s21, s11
	s_add_u32 s10, s17, s10
	s_addc_u32 s11, s18, s11
	s_add_i32 s24, s22, 0xc000
	s_mov_b32 s25, m0
	s_mov_b32 m0, s24
	s_nop 0
	global_load_lds_dwordx4 v168, s[10:11]
	s_mov_b32 m0, s25
	s_add_i32 s10, s22, 0xe000
	s_mov_b32 s11, m0
	s_mov_b32 m0, s10
	s_nop 0
	global_load_lds_dwordx4 v87, s[12:13]
	s_mov_b32 m0, s11
	s_cmp_lt_u32 s96, 4
	s_cbranch_scc1 .LBB0_308
.LBB0_330:
	s_add_i32 s10, s96, -4
	s_mov_b32 s11, s97
	s_lshl_b64 s[10:11], s[10:11], 14
	s_add_u32 s12, s20, s10
	s_addc_u32 s13, s21, s11
	s_add_u32 s10, s17, s10
	s_addc_u32 s11, s18, s11
	s_add_i32 s24, s22, 0x10000
	s_mov_b32 s25, m0
	s_mov_b32 m0, s24
	s_nop 0
	global_load_lds_dwordx4 v168, s[10:11]
	s_mov_b32 m0, s25
	s_add_i32 s10, s22, 0x12000
	s_mov_b32 s11, m0
	s_mov_b32 m0, s10
	s_nop 0
	global_load_lds_dwordx4 v87, s[12:13]
	s_mov_b32 m0, s11
	s_cmp_lt_u32 s96, 5
	s_cbranch_scc1 .LBB0_309
.LBB0_331:
	s_add_i32 s10, s96, -5
	s_mov_b32 s11, s97
	s_lshl_b64 s[10:11], s[10:11], 14
	s_add_u32 s12, s20, s10
	s_addc_u32 s13, s21, s11
	s_add_u32 s10, s17, s10
	s_addc_u32 s11, s18, s11
	s_add_i32 s24, s22, 0x14000
	s_mov_b32 s25, m0
	s_mov_b32 m0, s24
	s_nop 0
	global_load_lds_dwordx4 v168, s[10:11]
	s_mov_b32 m0, s25
	s_add_i32 s10, s22, 0x16000
	s_mov_b32 s11, m0
	s_mov_b32 m0, s10
	s_nop 0
	global_load_lds_dwordx4 v87, s[12:13]
	s_mov_b32 m0, s11
	s_cmp_lt_u32 s96, 6
	s_cbranch_scc1 .LBB0_310
.LBB0_332:
	s_add_i32 s10, s96, -6
	s_mov_b32 s11, s97
	s_lshl_b64 s[10:11], s[10:11], 14
	s_add_u32 s12, s20, s10
	s_addc_u32 s13, s21, s11
	s_add_u32 s10, s17, s10
	s_addc_u32 s11, s18, s11
	s_add_i32 s24, s22, 0x18000
	s_mov_b32 s25, m0
	s_mov_b32 m0, s24
	s_nop 0
	global_load_lds_dwordx4 v168, s[10:11]
	s_mov_b32 m0, s25
	s_add_i32 s10, s22, 0x1a000
	s_mov_b32 s11, m0
	s_mov_b32 m0, s10
	s_nop 0
	global_load_lds_dwordx4 v87, s[12:13]
	s_mov_b32 m0, s11
	s_cmp_lt_u32 s96, 7
	s_cbranch_scc0 .LBB0_311
	s_branch .LBB0_312
